# plus SWA QK read-ahead schedule and hand-written side-work row loops (conv gate rows, SWA merge rows)
# baseline (speedup 1.0000x reference)
; __device__ void swa_item(const Params& p, int item) {
;     ...
;   bf16x8 qf[4];
;   { long qrow = rowb + (long)(qb * 128 + w * 16 + c) * dil + r;
;     _Pragma("unroll") for (int kk = 0; kk < 4; ++kk) qf[kk] = *(const bf16x8*)(buf + qrow * 4608 + qcol + kk * 32 + q * 8); }
;   __syncthreads();
;   f32x4 S[9];
;   _Pragma("unroll") for (int ci = 0; ci < 9; ++ci) {
;     const int ct = w + ci;
;     f32x4 a = (f32x4){0.f, 0.f, 0.f, 0.f};
;     _Pragma("unroll") for (int kk = 0; kk < 4; ++kk) {
;       bf16x8 kf = *(const bf16x8*)(Ks + (ct * 16 + c) * 136 + kk * 32 + q * 8);
;       a = __builtin_amdgcn_mfma_f32_16x16x32_bf16(qf[kk], kf, a, 0, 0, 0);
;     }
;     S[ci] = a;
;   }
.LBB0_111:
	s_or_b64 exec, exec, s[12:13]
	s_movk_i32 s2, 0x1500
	v_lshlrev_b32_e32 v58, 4, v12
	v_mul_lo_u32 v2, v12, s2
	v_readlane_b32 s12, v254, 10
	v_add_u32_e32 v51, s35, v58
	v_readlane_b32 s26, v254, 13
	v_add_u32_e32 v57, s12, v2
	v_or_b32_e32 v2, v51, v55
	v_ashrrev_i32_e32 v3, 31, v2
	v_lshlrev_b64 v[2:3], s22, v[2:3]
	v_readlane_b32 s27, v254, 14
	v_mov_b64_e32 v[4:5], s[16:17]
	v_and_b32_e32 v52, 48, v50
	v_lshl_add_u64 v[2:3], v[2:3], 0, s[26:27]
	v_mad_u64_u32 v[4:5], s[2:3], v2, s89, v[4:5]
	v_mad_i32_i24 v5, v3, s89, v5
	v_lshl_add_u64 v[2:3], s[0:1], 1, v[4:5]
	v_mov_b32_e32 v53, v1
	v_lshl_add_u64 v[2:3], v[2:3], 0, v[52:53]
	global_load_dwordx4 v[46:49], v[2:3], off
	global_load_dwordx4 v[42:45], v[2:3], off offset:64
	global_load_dwordx4 v[38:41], v[2:3], off offset:128
	global_load_dwordx4 v[34:37], v[2:3], off offset:192
	v_add_u32_e32 v54, s12, v52
	v_or_b32_e32 v53, v58, v55
	s_movk_i32 s3, 0x110
	v_mad_u64_u32 v[30:31], s[0:1], v53, s3, v[54:55]
	s_waitcnt lgkmcnt(0)
	s_barrier
	v_bfe_u32 v56, v50, 4, 2
	s_cmp_lg_u32 s34, 0
	s_movk_i32 s2, 0x7f
	v_add_u32_e32 v62, 32, v53
	s_cselect_b64 s[14:15], -1, 0
	s_movk_i32 s18, 0x81
	v_add_u32_e32 v63, 48, v53
	v_add_u32_e32 v61, 16, v53
	v_add_u32_e32 v64, 64, v53
	v_add_u32_e32 v65, 0x50, v53
	v_add_u32_e32 v74, 0x60, v53
	v_add_u32_e32 v75, 0x70, v53
	v_and_b32_e32 v60, 63, v50
	v_add_u32_e32 v72, 0x80, v58
	v_or_b32_e32 v59, v72, v55
	v_mad_u64_u32 v[70:71], s[0:1], v59, s3, v[54:55]
	v_cmp_lt_i32_e64 s[0:1], s2, v53
	s_or_b64 s[12:13], s[14:15], s[0:1]
	v_cmp_lt_i32_e64 s[0:1], s2, v62
	s_or_b64 s[38:39], s[14:15], s[0:1]
	v_cmp_lt_i32_e64 s[0:1], s2, v63
	v_mov_b32_e32 v66, 0xf149f2ca
	s_or_b64 s[40:41], s[14:15], s[0:1]
	v_cmp_lt_i32_e64 s[0:1], s2, v64
	s_or_b64 s[42:43], s[14:15], s[0:1]
	v_mov_b32_e32 v144, v30
	ds_read_b128 v[76:79], v144 offset:0
	ds_read_b128 v[80:83], v144 offset:64
	ds_read_b128 v[84:87], v144 offset:128
	ds_read_b128 v[88:91], v144 offset:192
	ds_read_b128 v[92:95], v144 offset:4352
	ds_read_b128 v[96:99], v144 offset:4416
	ds_read_b128 v[100:103], v144 offset:4480
	ds_read_b128 v[104:107], v144 offset:4544
	ds_read_b128 v[108:111], v144 offset:8704
	ds_read_b128 v[112:115], v144 offset:8768
	ds_read_b128 v[116:119], v144 offset:8832
	ds_read_b128 v[120:123], v144 offset:8896
	ds_read_b128 v[124:127], v144 offset:13056
	ds_read_b128 v[128:131], v144 offset:13120
	ds_read_b128 v[132:135], v144 offset:13184
	s_waitcnt vmcnt(0)
	s_waitcnt lgkmcnt(14)
	v_mfma_f32_16x16x32_bf16 v[2:5], v[46:49], v[76:79], 0
	ds_read_b128 v[136:139], v144 offset:13248
	s_waitcnt lgkmcnt(14)
	v_mfma_f32_16x16x32_bf16 v[2:5], v[42:45], v[80:83], v[2:5]
	ds_read_b128 v[76:79], v144 offset:17408
	s_waitcnt lgkmcnt(14)
	v_mfma_f32_16x16x32_bf16 v[2:5], v[38:41], v[84:87], v[2:5]
	ds_read_b128 v[80:83], v144 offset:17472
	s_waitcnt lgkmcnt(14)
	v_mfma_f32_16x16x32_bf16 v[2:5], v[34:37], v[88:91], v[2:5]
	ds_read_b128 v[84:87], v144 offset:17536
	s_waitcnt lgkmcnt(14)
	v_mfma_f32_16x16x32_bf16 v[6:9], v[46:49], v[92:95], 0
	ds_read_b128 v[88:91], v144 offset:17600
	s_waitcnt lgkmcnt(14)
	v_mfma_f32_16x16x32_bf16 v[6:9], v[42:45], v[96:99], v[6:9]
	ds_read_b128 v[92:95], v144 offset:21760
	s_waitcnt lgkmcnt(14)
	v_mfma_f32_16x16x32_bf16 v[6:9], v[38:41], v[100:103], v[6:9]
	ds_read_b128 v[96:99], v144 offset:21824
	s_waitcnt lgkmcnt(14)
	v_mfma_f32_16x16x32_bf16 v[6:9], v[34:37], v[104:107], v[6:9]
	ds_read_b128 v[100:103], v144 offset:21888
	s_waitcnt lgkmcnt(14)
	v_mfma_f32_16x16x32_bf16 v[10:13], v[46:49], v[108:111], 0
	ds_read_b128 v[104:107], v144 offset:21952
	s_waitcnt lgkmcnt(14)
	v_mfma_f32_16x16x32_bf16 v[10:13], v[42:45], v[112:115], v[10:13]
	ds_read_b128 v[108:111], v144 offset:26112
	s_waitcnt lgkmcnt(14)
	v_mfma_f32_16x16x32_bf16 v[10:13], v[38:41], v[116:119], v[10:13]
	ds_read_b128 v[112:115], v144 offset:26176
	s_waitcnt lgkmcnt(14)
	v_mfma_f32_16x16x32_bf16 v[10:13], v[34:37], v[120:123], v[10:13]
	ds_read_b128 v[116:119], v144 offset:26240
	s_waitcnt lgkmcnt(14)
	v_mfma_f32_16x16x32_bf16 v[14:17], v[46:49], v[124:127], 0
	ds_read_b128 v[120:123], v144 offset:26304
	s_waitcnt lgkmcnt(14)
	v_mfma_f32_16x16x32_bf16 v[14:17], v[42:45], v[128:131], v[14:17]
	ds_read_b128 v[124:127], v144 offset:30464
	s_waitcnt lgkmcnt(14)
	v_mfma_f32_16x16x32_bf16 v[14:17], v[38:41], v[132:135], v[14:17]
	ds_read_b128 v[128:131], v144 offset:30528
	s_waitcnt lgkmcnt(14)
	v_mfma_f32_16x16x32_bf16 v[14:17], v[34:37], v[136:139], v[14:17]
	ds_read_b128 v[132:135], v144 offset:30592
	s_waitcnt lgkmcnt(14)
	v_mfma_f32_16x16x32_bf16 v[18:21], v[46:49], v[76:79], 0
	ds_read_b128 v[136:139], v144 offset:30656
	s_waitcnt lgkmcnt(14)
	v_mfma_f32_16x16x32_bf16 v[18:21], v[42:45], v[80:83], v[18:21]
	ds_read_b128 v[76:79], v144 offset:34816
	s_waitcnt lgkmcnt(14)
	v_mfma_f32_16x16x32_bf16 v[18:21], v[38:41], v[84:87], v[18:21]
	ds_read_b128 v[80:83], v144 offset:34880
	s_waitcnt lgkmcnt(14)
	v_mfma_f32_16x16x32_bf16 v[18:21], v[34:37], v[88:91], v[18:21]
	ds_read_b128 v[84:87], v144 offset:34944
	s_waitcnt lgkmcnt(14)
	v_mfma_f32_16x16x32_bf16 v[22:25], v[46:49], v[92:95], 0
	ds_read_b128 v[88:91], v144 offset:35008
	s_waitcnt lgkmcnt(14)
	v_mfma_f32_16x16x32_bf16 v[22:25], v[42:45], v[96:99], v[22:25]
	s_waitcnt lgkmcnt(13)
	v_mfma_f32_16x16x32_bf16 v[22:25], v[38:41], v[100:103], v[22:25]
	s_waitcnt lgkmcnt(12)
	v_mfma_f32_16x16x32_bf16 v[22:25], v[34:37], v[104:107], v[22:25]
	s_waitcnt lgkmcnt(11)
	v_mfma_f32_16x16x32_bf16 v[26:29], v[46:49], v[108:111], 0
	s_waitcnt lgkmcnt(10)
	v_mfma_f32_16x16x32_bf16 v[26:29], v[42:45], v[112:115], v[26:29]
	s_waitcnt lgkmcnt(9)
; __device__ __forceinline__ float fexp(float x) { return __builtin_amdgcn_exp2f(x * 1.4426950408889634f); }
; #define SHX(v, m) shx_((v), (m), lane)
; __device__ void swa_item(const Params& p, int item) {
;     ...
;   f32x4 S[9];
;   _Pragma("unroll") for (int ci = 0; ci < 9; ++ci) {
;     const int ct = w + ci;
;     f32x4 a = (f32x4){0.f, 0.f, 0.f, 0.f};
;     _Pragma("unroll") for (int kk = 0; kk < 4; ++kk) {
;       bf16x8 kf = *(const bf16x8*)(Ks + (ct * 16 + c) * 136 + kk * 32 + q * 8);
;       a = __builtin_amdgcn_mfma_f32_16x16x32_bf16(qf[kk], kf, a, 0, 0, 0);
;     }
;     S[ci] = a;
;   }
;   float mx[4], ls[4];
;   _Pragma("unroll") for (int jj = 0; jj < 4; ++jj) {
;     const int qi = w * 16 + q * 4 + jj;
;     float m = -1e30f;
;     _Pragma("unroll") for (int ci = 0; ci < 9; ++ci) {
;       int kj = (w + ci) * 16 + c; int dist = qi + 128 - kj;
;       bool valid = (dist >= 0) && (dist <= 128) && (qb > 0 || kj >= 128);
;       float s = valid ? S[ci][jj] : -1e30f;
;       S[ci][jj] = s; m = fmaxf(m, s);
;     }
;     m = fmaxf(m, SHX(m, 1)); m = fmaxf(m, SHX(m, 2)); m = fmaxf(m, SHX(m, 4)); m = fmaxf(m, SHX(m, 8));
;     float l = 0.f;
;     _Pragma("unroll") for (int ci = 0; ci < 9; ++ci) {
;       float s = S[ci][jj];
;       float pv = (s > -1e29f) ? fexp(s - m) : 0.f;
;       S[ci][jj] = pv; l += pv;
;     }
;     l += SHX(l, 1); l += SHX(l, 2); l += SHX(l, 4); l += SHX(l, 8);
;     mx[jj] = m; ls[jj] = l;
;   }
;   __syncthreads();
	v_mfma_f32_16x16x32_bf16 v[26:29], v[38:41], v[116:119], v[26:29]
	s_waitcnt lgkmcnt(8)
	v_mfma_f32_16x16x32_bf16 v[26:29], v[34:37], v[120:123], v[26:29]
	s_waitcnt lgkmcnt(7)
	v_mfma_f32_16x16x32_bf16 v[30:33], v[46:49], v[124:127], 0
	s_waitcnt lgkmcnt(6)
	v_mfma_f32_16x16x32_bf16 v[30:33], v[42:45], v[128:131], v[30:33]
	s_waitcnt lgkmcnt(5)
	v_mfma_f32_16x16x32_bf16 v[30:33], v[38:41], v[132:135], v[30:33]
	s_waitcnt lgkmcnt(4)
	v_mfma_f32_16x16x32_bf16 v[30:33], v[34:37], v[136:139], v[30:33]
	s_waitcnt lgkmcnt(3)
	v_mfma_f32_16x16x32_bf16 v[140:143], v[46:49], v[76:79], 0
	s_waitcnt lgkmcnt(2)
	v_mfma_f32_16x16x32_bf16 v[140:143], v[42:45], v[80:83], v[140:143]
	s_waitcnt lgkmcnt(1)
	v_mfma_f32_16x16x32_bf16 v[140:143], v[38:41], v[84:87], v[140:143]
	s_waitcnt lgkmcnt(0)
	v_mfma_f32_16x16x32_bf16 v[34:37], v[34:37], v[88:91], v[140:143]
	v_cmp_lt_i32_e64 s[0:1], s2, v65
	s_nop 1
	v_lshlrev_b32_e32 v38, 2, v56
	v_or_b32_e32 v43, v72, v38
	v_sub_u32_e32 v44, v43, v53
	v_cmp_gt_u32_e32 vcc, s18, v44
	s_and_b64 vcc, vcc, s[12:13]
	v_cndmask_b32_e64 v45, v66, v10, s[38:39]
	v_cndmask_b32_e32 v2, v66, v2, vcc
	v_cmp_lt_i32_e32 vcc, s2, v61
	v_max_f32_e32 v44, v2, v2
	s_or_b64 vcc, s[14:15], vcc
	v_max_f32_e32 v44, 0xf149f2ca, v44
	v_cndmask_b32_e32 v6, v66, v6, vcc
	s_or_b64 s[44:45], s[14:15], s[0:1]
	v_cmp_lt_i32_e64 s[0:1], s2, v74
	v_max3_f32 v10, v44, v6, v45
	v_cndmask_b32_e64 v44, v66, v18, s[42:43]
	s_or_b64 s[46:47], s[14:15], s[0:1]
	v_cmp_lt_i32_e64 s[0:1], s2, v75
	v_sub_u32_e32 v18, v38, v55
	v_cmp_lt_i32_e64 s[50:51], s2, v59
	v_cndmask_b32_e64 v14, v66, v14, s[40:41]
	s_or_b64 s[48:49], s[14:15], s[0:1]
	v_cmp_gt_u32_e64 s[0:1], s18, v18
	s_or_b64 s[14:15], s[14:15], s[50:51]
	v_max3_f32 v10, v10, v14, v44
	v_cndmask_b32_e64 v46, v66, v22, s[44:45]
	v_cndmask_b32_e64 v26, v66, v26, s[46:47]
	s_and_b64 s[0:1], s[0:1], s[14:15]
	v_lshlrev_b32_e32 v39, 2, v60
	v_max3_f32 v10, v10, v46, v26
	v_cndmask_b32_e64 v47, v66, v30, s[48:49]
	v_cndmask_b32_e64 v48, v66, v34, s[0:1]
	v_xor_b32_e32 v42, 4, v39
	v_max3_f32 v10, v10, v47, v48
	ds_bpermute_b32 v18, v42, v10
	v_xor_b32_e32 v41, 8, v39
	v_xor_b32_e32 v40, 16, v39
	v_xor_b32_e32 v39, 32, v39
	s_mov_b32 s2, 0xefa18f08
	s_waitcnt lgkmcnt(0)
	v_max_f32_e32 v18, v18, v18
	v_max_f32_e32 v10, v10, v18
	ds_bpermute_b32 v18, v41, v10
	v_cmp_lt_f32_e64 s[0:1], s2, v2
	v_cndmask_b32_e32 v7, v66, v7, vcc
	v_cndmask_b32_e64 v15, v66, v15, s[40:41]
	v_cndmask_b32_e64 v49, v66, v23, s[44:45]
	s_waitcnt lgkmcnt(0)
	v_max_f32_e32 v18, v18, v18
	v_max_f32_e32 v10, v10, v18
	ds_bpermute_b32 v18, v40, v10
	v_cndmask_b32_e64 v27, v66, v27, s[46:47]
	v_cndmask_b32_e64 v54, v66, v31, s[48:49]
	v_cndmask_b32_e32 v8, v66, v8, vcc
	v_cndmask_b32_e64 v12, v66, v12, s[38:39]
	s_waitcnt lgkmcnt(0)
	v_max_f32_e32 v18, v18, v18
	v_max_f32_e32 v10, v10, v18
	ds_bpermute_b32 v18, v39, v10
	v_cndmask_b32_e64 v60, v66, v32, s[48:49]
	v_cndmask_b32_e64 v16, v66, v16, s[40:41]
	v_cndmask_b32_e64 v20, v66, v20, s[42:43]
	v_cndmask_b32_e64 v28, v66, v28, s[46:47]
	s_waitcnt lgkmcnt(0)
	v_max_f32_e32 v18, v18, v18
	v_max_f32_e32 v22, v10, v18
	v_sub_f32_e32 v2, v2, v22
	v_mul_f32_e32 v2, 0x3fb8aa3b, v2
	v_exp_f32_e32 v2, v2
	v_sub_f32_e32 v34, v46, v22
	v_mul_f32_e32 v34, 0x3fb8aa3b, v34
	v_exp_f32_e32 v34, v34
	v_cndmask_b32_e64 v2, 0, v2, s[0:1]
	v_cmp_lt_f32_e64 s[0:1], s2, v6
	v_sub_f32_e32 v6, v6, v22
	v_mul_f32_e32 v6, 0x3fb8aa3b, v6
	v_exp_f32_e32 v6, v6
	v_add_f32_e32 v18, 0, v2
	v_cndmask_b32_e32 v9, v66, v9, vcc
	v_cndmask_b32_e64 v13, v66, v13, s[38:39]
	v_cndmask_b32_e64 v10, 0, v6, s[0:1]
	v_sub_f32_e32 v6, v45, v22
	v_mul_f32_e32 v6, 0x3fb8aa3b, v6
	v_exp_f32_e32 v6, v6
	v_cmp_lt_f32_e64 s[0:1], s2, v45
	v_add_f32_e32 v18, v10, v18
	v_cndmask_b32_e64 v17, v66, v17, s[40:41]
	v_cndmask_b32_e64 v6, 0, v6, s[0:1]
	v_cmp_lt_f32_e64 s[0:1], s2, v14
	v_sub_f32_e32 v14, v14, v22
	v_mul_f32_e32 v14, 0x3fb8aa3b, v14
	v_exp_f32_e32 v14, v14
	v_add_f32_e32 v30, v6, v18
	v_cndmask_b32_e64 v21, v66, v21, s[42:43]
	v_cndmask_b32_e64 v29, v66, v29, s[46:47]
	v_cndmask_b32_e64 v18, 0, v14, s[0:1]
	v_sub_f32_e32 v14, v44, v22
	v_mul_f32_e32 v14, 0x3fb8aa3b, v14
	v_exp_f32_e32 v14, v14
	v_cmp_lt_f32_e64 s[0:1], s2, v44
	v_add_f32_e32 v30, v18, v30
	v_cndmask_b32_e64 v33, v66, v33, s[48:49]
	v_cndmask_b32_e64 v14, 0, v14, s[0:1]
	v_cmp_lt_f32_e64 s[0:1], s2, v46
	v_add_f32_e32 v30, v14, v30
	s_nop 0
	v_cndmask_b32_e64 v34, 0, v34, s[0:1]
	v_cmp_lt_f32_e64 s[0:1], s2, v26
	v_sub_f32_e32 v26, v26, v22
	v_mul_f32_e32 v26, 0x3fb8aa3b, v26
	v_exp_f32_e32 v26, v26
	v_add_f32_e32 v44, v34, v30
	s_barrier
; __device__ __forceinline__ float fexp(float x) { return __builtin_amdgcn_exp2f(x * 1.4426950408889634f); }
; #define SHX(v, m) shx_((v), (m), lane)
; __device__ void swa_item(const Params& p, int item) {
;     ...
;   _Pragma("unroll") for (int jj = 0; jj < 4; ++jj) {
;     const int qi = w * 16 + q * 4 + jj;
;     float m = -1e30f;
;     _Pragma("unroll") for (int ci = 0; ci < 9; ++ci) {
;       int kj = (w + ci) * 16 + c; int dist = qi + 128 - kj;
;       bool valid = (dist >= 0) && (dist <= 128) && (qb > 0 || kj >= 128);
;       float s = valid ? S[ci][jj] : -1e30f;
;       S[ci][jj] = s; m = fmaxf(m, s);
;     }
;     m = fmaxf(m, SHX(m, 1)); m = fmaxf(m, SHX(m, 2)); m = fmaxf(m, SHX(m, 4)); m = fmaxf(m, SHX(m, 8));
;     float l = 0.f;
;     _Pragma("unroll") for (int ci = 0; ci < 9; ++ci) {
;       float s = S[ci][jj];
;       float pv = (s > -1e29f) ? fexp(s - m) : 0.f;
;       S[ci][jj] = pv; l += pv;
;     }
;     l += SHX(l, 1); l += SHX(l, 2); l += SHX(l, 4); l += SHX(l, 8);
;     mx[jj] = m; ls[jj] = l;
;   }
	v_cndmask_b32_e64 v30, 0, v26, s[0:1]
	v_add_f32_e32 v26, v30, v44
	v_sub_f32_e32 v44, v47, v22
	v_mul_f32_e32 v44, 0x3fb8aa3b, v44
	v_exp_f32_e32 v44, v44
	v_cmp_lt_f32_e64 s[0:1], s2, v47
	s_nop 1
	v_cndmask_b32_e64 v45, 0, v44, s[0:1]
	v_sub_f32_e32 v44, v48, v22
	v_mul_f32_e32 v44, 0x3fb8aa3b, v44
	v_exp_f32_e32 v44, v44
	v_cmp_lt_f32_e64 s[0:1], s2, v48
	v_add_f32_e32 v26, v45, v26
	v_cndmask_b32_e64 v48, v66, v11, s[38:39]
	v_cndmask_b32_e64 v44, 0, v44, s[0:1]
	v_add_f32_e32 v26, v44, v26
	ds_bpermute_b32 v46, v42, v26
	s_waitcnt lgkmcnt(0)
	v_add_f32_e32 v26, v26, v46
	ds_bpermute_b32 v46, v41, v26
	s_waitcnt lgkmcnt(0)
	v_add_f32_e32 v26, v26, v46
	ds_bpermute_b32 v46, v40, v26
	s_waitcnt lgkmcnt(0)
	v_add_f32_e32 v26, v26, v46
	ds_bpermute_b32 v46, v39, v26
	s_waitcnt lgkmcnt(0)
	v_add_f32_e32 v26, v26, v46
	v_or_b32_e32 v46, 1, v43
	v_sub_u32_e32 v47, v46, v53
	v_cmp_gt_u32_e64 s[0:1], s18, v47
	s_and_b64 s[0:1], s[0:1], s[12:13]
	s_nop 0
	v_cndmask_b32_e64 v3, v66, v3, s[0:1]
	v_max_f32_e32 v47, v3, v3
	v_max_f32_e32 v47, 0xf149f2ca, v47
	v_max3_f32 v11, v47, v7, v48
	v_cndmask_b32_e64 v47, v66, v19, s[42:43]
	v_sub_u32_e32 v19, v46, v59
	v_cmp_gt_u32_e64 s[0:1], s18, v19
	v_max3_f32 v11, v11, v15, v47
	s_and_b64 s[0:1], s[0:1], s[14:15]
	v_max3_f32 v11, v11, v49, v27
	v_cndmask_b32_e64 v35, v66, v35, s[0:1]
	v_max3_f32 v11, v11, v54, v35
	ds_bpermute_b32 v19, v42, v11
	v_cmp_lt_f32_e64 s[0:1], s2, v3
	s_waitcnt lgkmcnt(0)
	v_max_f32_e32 v19, v19, v19
	v_max_f32_e32 v11, v11, v19
	ds_bpermute_b32 v19, v41, v11
	s_waitcnt lgkmcnt(0)
	v_max_f32_e32 v19, v19, v19
	v_max_f32_e32 v11, v11, v19
	ds_bpermute_b32 v19, v40, v11
	s_waitcnt lgkmcnt(0)
	v_max_f32_e32 v19, v19, v19
	v_max_f32_e32 v11, v11, v19
	ds_bpermute_b32 v19, v39, v11
	s_waitcnt lgkmcnt(0)
	v_max_f32_e32 v19, v19, v19
	v_max_f32_e32 v23, v11, v19
	v_sub_f32_e32 v3, v3, v23
	v_mul_f32_e32 v3, 0x3fb8aa3b, v3
	v_exp_f32_e32 v3, v3
	v_sub_f32_e32 v46, v49, v23
	v_mul_f32_e32 v46, 0x3fb8aa3b, v46
	v_exp_f32_e32 v46, v46
	v_cndmask_b32_e64 v3, 0, v3, s[0:1]
	v_cmp_lt_f32_e64 s[0:1], s2, v7
	v_sub_f32_e32 v7, v7, v23
	v_mul_f32_e32 v7, 0x3fb8aa3b, v7
	v_exp_f32_e32 v7, v7
	v_add_f32_e32 v19, 0, v3
	v_cndmask_b32_e64 v11, 0, v7, s[0:1]
	v_sub_f32_e32 v7, v48, v23
	v_mul_f32_e32 v7, 0x3fb8aa3b, v7
	v_exp_f32_e32 v7, v7
	v_cmp_lt_f32_e64 s[0:1], s2, v48
	v_add_f32_e32 v19, v11, v19
	s_nop 0
	v_cndmask_b32_e64 v7, 0, v7, s[0:1]
	v_cmp_lt_f32_e64 s[0:1], s2, v15
	v_sub_f32_e32 v15, v15, v23
	v_mul_f32_e32 v15, 0x3fb8aa3b, v15
	v_exp_f32_e32 v15, v15
	v_add_f32_e32 v31, v7, v19
	v_cndmask_b32_e64 v19, 0, v15, s[0:1]
	v_sub_f32_e32 v15, v47, v23
	v_mul_f32_e32 v15, 0x3fb8aa3b, v15
	v_exp_f32_e32 v15, v15
	v_cmp_lt_f32_e64 s[0:1], s2, v47
	v_add_f32_e32 v31, v19, v31
	s_nop 0
	v_cndmask_b32_e64 v15, 0, v15, s[0:1]
	v_cmp_lt_f32_e64 s[0:1], s2, v49
	v_add_f32_e32 v31, v15, v31
	s_nop 0
	v_cndmask_b32_e64 v46, 0, v46, s[0:1]
	v_cmp_lt_f32_e64 s[0:1], s2, v27
	v_sub_f32_e32 v27, v27, v23
	v_mul_f32_e32 v27, 0x3fb8aa3b, v27
	v_exp_f32_e32 v27, v27
	v_add_f32_e32 v47, v46, v31
	v_cndmask_b32_e64 v31, 0, v27, s[0:1]
	v_add_f32_e32 v27, v31, v47
	v_sub_f32_e32 v47, v54, v23
	v_mul_f32_e32 v47, 0x3fb8aa3b, v47
	v_exp_f32_e32 v47, v47
	v_cmp_lt_f32_e64 s[0:1], s2, v54
	v_cndmask_b32_e64 v54, v66, v24, s[44:45]
	s_nop 0
	v_cndmask_b32_e64 v47, 0, v47, s[0:1]
	v_cmp_lt_f32_e64 s[0:1], s2, v35
	v_sub_f32_e32 v35, v35, v23
	v_mul_f32_e32 v35, 0x3fb8aa3b, v35
	v_exp_f32_e32 v35, v35
	v_add_f32_e32 v27, v47, v27
	v_cndmask_b32_e64 v35, 0, v35, s[0:1]
	v_add_f32_e32 v27, v35, v27
	ds_bpermute_b32 v48, v42, v27
	s_waitcnt lgkmcnt(0)
	v_add_f32_e32 v27, v27, v48
	ds_bpermute_b32 v48, v41, v27
	s_waitcnt lgkmcnt(0)
	v_add_f32_e32 v27, v27, v48
	ds_bpermute_b32 v48, v40, v27
	s_waitcnt lgkmcnt(0)
	v_add_f32_e32 v27, v27, v48
	ds_bpermute_b32 v48, v39, v27
	s_waitcnt lgkmcnt(0)
	v_add_f32_e32 v27, v27, v48
	v_or_b32_e32 v48, 2, v43
	v_sub_u32_e32 v49, v48, v53
	v_cmp_gt_u32_e64 s[0:1], s18, v49
	s_and_b64 s[0:1], s[0:1], s[12:13]
	v_sub_u32_e32 v32, v48, v59
	v_cndmask_b32_e64 v4, v66, v4, s[0:1]
	v_max_f32_e32 v49, v4, v4
	v_max_f32_e32 v49, 0xf149f2ca, v49
	v_max3_f32 v49, v49, v8, v12
	v_cmp_gt_u32_e64 s[0:1], s18, v32
	v_max3_f32 v49, v49, v16, v20
	s_and_b64 s[0:1], s[0:1], s[14:15]
	v_max3_f32 v24, v49, v54, v28
	v_cndmask_b32_e64 v61, v66, v36, s[0:1]
	v_max3_f32 v24, v24, v60, v61
	ds_bpermute_b32 v32, v42, v24
	v_cmp_lt_f32_e64 s[0:1], s2, v4
	v_or_b32_e32 v43, 3, v43
	v_sub_u32_e32 v53, v43, v53
	v_sub_u32_e32 v43, v43, v59
	s_waitcnt lgkmcnt(0)
	v_max_f32_e32 v32, v32, v32
	v_max_f32_e32 v24, v24, v32
	ds_bpermute_b32 v32, v41, v24
	v_cmp_gt_u32_e32 vcc, s18, v43
	s_and_b64 vcc, vcc, s[14:15]
	s_waitcnt lgkmcnt(0)
	v_max_f32_e32 v32, v32, v32
	v_max_f32_e32 v24, v24, v32
	ds_bpermute_b32 v32, v40, v24
	v_cndmask_b32_e32 v37, v66, v37, vcc
	s_waitcnt lgkmcnt(0)
	v_max_f32_e32 v32, v32, v32
	v_max_f32_e32 v24, v24, v32
	ds_bpermute_b32 v32, v39, v24
	s_waitcnt lgkmcnt(0)
; __device__ __forceinline__ float fexp(float x) { return __builtin_amdgcn_exp2f(x * 1.4426950408889634f); }
; #define SHX(v, m) shx_((v), (m), lane)
; __device__ void swa_item(const Params& p, int item) {
;     ...
;   _Pragma("unroll") for (int jj = 0; jj < 4; ++jj) {
;     const int qi = w * 16 + q * 4 + jj;
;     float m = -1e30f;
;     _Pragma("unroll") for (int ci = 0; ci < 9; ++ci) {
;       int kj = (w + ci) * 16 + c; int dist = qi + 128 - kj;
;       bool valid = (dist >= 0) && (dist <= 128) && (qb > 0 || kj >= 128);
;       float s = valid ? S[ci][jj] : -1e30f;
;       S[ci][jj] = s; m = fmaxf(m, s);
;     }
;     m = fmaxf(m, SHX(m, 1)); m = fmaxf(m, SHX(m, 2)); m = fmaxf(m, SHX(m, 4)); m = fmaxf(m, SHX(m, 8));
;     float l = 0.f;
;     _Pragma("unroll") for (int ci = 0; ci < 9; ++ci) {
;       float s = S[ci][jj];
;       float pv = (s > -1e29f) ? fexp(s - m) : 0.f;
;       S[ci][jj] = pv; l += pv;
;     }
;     l += SHX(l, 1); l += SHX(l, 2); l += SHX(l, 4); l += SHX(l, 8);
;     mx[jj] = m; ls[jj] = l;
;   }
;   __syncthreads();
;   _Pragma("unroll") for (int ci = 0; ci < 9; ++ci) _Pragma("unroll") for (int jj = 0; jj < 4; ++jj) Pl[(q * 4 + jj) * 168 + ci * 16 + c] = f2bf(S[ci][jj]);
	v_max_f32_e32 v32, v32, v32
	v_max_f32_e32 v24, v24, v32
	v_sub_f32_e32 v4, v4, v24
	v_mul_f32_e32 v4, 0x3fb8aa3b, v4
	v_exp_f32_e32 v4, v4
	s_nop 0
	v_cndmask_b32_e64 v4, 0, v4, s[0:1]
	v_cmp_lt_f32_e64 s[0:1], s2, v8
	v_sub_f32_e32 v8, v8, v24
	v_mul_f32_e32 v8, 0x3fb8aa3b, v8
	v_exp_f32_e32 v8, v8
	v_add_f32_e32 v32, 0, v4
	v_cndmask_b32_e64 v8, 0, v8, s[0:1]
	v_cmp_lt_f32_e64 s[0:1], s2, v12
	v_sub_f32_e32 v12, v12, v24
	v_mul_f32_e32 v12, 0x3fb8aa3b, v12
	v_exp_f32_e32 v12, v12
	v_add_f32_e32 v32, v8, v32
	v_cndmask_b32_e64 v12, 0, v12, s[0:1]
	v_cmp_lt_f32_e64 s[0:1], s2, v16
	v_sub_f32_e32 v16, v16, v24
	v_mul_f32_e32 v16, 0x3fb8aa3b, v16
	v_exp_f32_e32 v16, v16
	v_add_f32_e32 v32, v12, v32
	v_cndmask_b32_e64 v16, 0, v16, s[0:1]
	v_cmp_lt_f32_e64 s[0:1], s2, v20
	v_sub_f32_e32 v20, v20, v24
	v_mul_f32_e32 v20, 0x3fb8aa3b, v20
	v_exp_f32_e32 v20, v20
	v_add_f32_e32 v36, v16, v32
	v_cndmask_b32_e64 v32, 0, v20, s[0:1]
	v_add_f32_e32 v20, v32, v36
	v_sub_f32_e32 v36, v54, v24
	v_mul_f32_e32 v36, 0x3fb8aa3b, v36
	v_exp_f32_e32 v36, v36
	v_cmp_lt_f32_e64 s[0:1], s2, v54
	s_nop 1
	v_cndmask_b32_e64 v49, 0, v36, s[0:1]
	v_cmp_lt_f32_e64 s[0:1], s2, v28
	v_sub_f32_e32 v28, v28, v24
	v_mul_f32_e32 v28, 0x3fb8aa3b, v28
	v_exp_f32_e32 v28, v28
	v_add_f32_e32 v20, v49, v20
	v_cndmask_b32_e64 v48, 0, v28, s[0:1]
	v_sub_f32_e32 v28, v60, v24
	v_mul_f32_e32 v28, 0x3fb8aa3b, v28
	v_exp_f32_e32 v28, v28
	v_cmp_lt_f32_e64 s[0:1], s2, v60
	v_add_f32_e32 v20, v48, v20
	s_nop 0
	v_cndmask_b32_e64 v36, 0, v28, s[0:1]
	v_add_f32_e32 v28, v36, v20
	v_sub_f32_e32 v20, v61, v24
	v_mul_f32_e32 v20, 0x3fb8aa3b, v20
	v_exp_f32_e32 v20, v20
	v_cmp_lt_f32_e64 s[0:1], s2, v61
	s_nop 1
	v_cndmask_b32_e64 v20, 0, v20, s[0:1]
	v_add_f32_e32 v28, v20, v28
	ds_bpermute_b32 v54, v42, v28
	v_cmp_gt_u32_e64 s[0:1], s18, v53
	s_and_b64 s[0:1], s[0:1], s[12:13]
	s_waitcnt lgkmcnt(0)
	v_add_f32_e32 v28, v28, v54
	ds_bpermute_b32 v54, v41, v28
	v_cndmask_b32_e64 v5, v66, v5, s[0:1]
	v_max_f32_e32 v53, v5, v5
	v_max_f32_e32 v53, 0xf149f2ca, v53
	v_max3_f32 v53, v53, v9, v13
	s_waitcnt lgkmcnt(0)
	v_add_f32_e32 v28, v28, v54
	ds_bpermute_b32 v54, v40, v28
	v_max3_f32 v53, v53, v17, v21
	v_cmp_lt_f32_e32 vcc, s2, v5
	s_movk_i32 s0, 0x540
	s_waitcnt lgkmcnt(0)
	v_add_f32_e32 v28, v28, v54
	ds_bpermute_b32 v54, v39, v28
	s_waitcnt lgkmcnt(0)
	v_add_f32_e32 v28, v28, v54
	v_cndmask_b32_e64 v54, v66, v25, s[44:45]
	v_max3_f32 v25, v53, v54, v29
	v_max3_f32 v25, v25, v33, v37
	ds_bpermute_b32 v43, v42, v25
	s_waitcnt lgkmcnt(0)
	v_max_f32_e32 v43, v43, v43
	v_max_f32_e32 v25, v25, v43
	ds_bpermute_b32 v43, v41, v25
	s_waitcnt lgkmcnt(0)
	v_max_f32_e32 v43, v43, v43
	v_max_f32_e32 v25, v25, v43
	ds_bpermute_b32 v43, v40, v25
	s_waitcnt lgkmcnt(0)
	v_max_f32_e32 v43, v43, v43
	v_max_f32_e32 v25, v25, v43
	ds_bpermute_b32 v43, v39, v25
	s_waitcnt lgkmcnt(0)
	v_max_f32_e32 v43, v43, v43
	v_max_f32_e32 v25, v25, v43
	v_sub_f32_e32 v5, v5, v25
	v_mul_f32_e32 v5, 0x3fb8aa3b, v5
	v_exp_f32_e32 v5, v5
	v_sub_f32_e32 v53, v54, v25
	v_mul_f32_e32 v53, 0x3fb8aa3b, v53
	v_exp_f32_e32 v53, v53
	v_cndmask_b32_e32 v5, 0, v5, vcc
	v_cmp_lt_f32_e32 vcc, s2, v9
	v_sub_f32_e32 v9, v9, v25
	v_mul_f32_e32 v9, 0x3fb8aa3b, v9
	v_exp_f32_e32 v9, v9
	v_add_f32_e32 v43, 0, v5
	v_cndmask_b32_e32 v9, 0, v9, vcc
	v_cmp_lt_f32_e32 vcc, s2, v13
	v_sub_f32_e32 v13, v13, v25
	v_mul_f32_e32 v13, 0x3fb8aa3b, v13
	v_exp_f32_e32 v13, v13
	v_add_f32_e32 v43, v9, v43
	v_cndmask_b32_e32 v13, 0, v13, vcc
	v_cmp_lt_f32_e32 vcc, s2, v17
	v_sub_f32_e32 v17, v17, v25
	v_mul_f32_e32 v17, 0x3fb8aa3b, v17
	v_exp_f32_e32 v17, v17
	v_add_f32_e32 v43, v13, v43
	v_cndmask_b32_e32 v17, 0, v17, vcc
	v_cmp_lt_f32_e32 vcc, s2, v21
	v_sub_f32_e32 v21, v21, v25
	v_mul_f32_e32 v21, 0x3fb8aa3b, v21
	v_exp_f32_e32 v21, v21
	v_add_f32_e32 v43, v17, v43
	v_cndmask_b32_e32 v21, 0, v21, vcc
	v_cmp_lt_f32_e32 vcc, s2, v54
	v_add_f32_e32 v43, v21, v43
	s_nop 0
	v_cndmask_b32_e32 v53, 0, v53, vcc
	v_cmp_lt_f32_e32 vcc, s2, v29
	v_sub_f32_e32 v29, v29, v25
	v_mul_f32_e32 v29, 0x3fb8aa3b, v29
	v_exp_f32_e32 v29, v29
	v_add_f32_e32 v43, v53, v43
	v_cndmask_b32_e32 v54, 0, v29, vcc
	v_cmp_lt_f32_e32 vcc, s2, v33
	v_sub_f32_e32 v33, v33, v25
	v_mul_f32_e32 v33, 0x3fb8aa3b, v33
	v_exp_f32_e32 v33, v33
	v_add_f32_e32 v29, v54, v43
	v_or_b32_e32 v43, 1, v38
	v_cndmask_b32_e32 v33, 0, v33, vcc
	v_cmp_lt_f32_e32 vcc, s2, v37
	v_sub_f32_e32 v37, v37, v25
	v_mul_f32_e32 v37, 0x3fb8aa3b, v37
	v_exp_f32_e32 v37, v37
	v_add_f32_e32 v29, v33, v29
	s_movk_i32 s2, 0xc0
	v_cndmask_b32_e32 v37, 0, v37, vcc
	v_add_f32_e32 v29, v37, v29
	ds_bpermute_b32 v42, v42, v29
	s_waitcnt lgkmcnt(0)
	v_add_f32_e32 v29, v29, v42
	ds_bpermute_b32 v41, v41, v29
	s_waitcnt lgkmcnt(0)
	v_add_f32_e32 v29, v29, v41
	ds_bpermute_b32 v40, v40, v29
	v_bfe_u32 v41, v2, 16, 1
	v_add3_u32 v2, v2, v41, s72
	v_mul_u32_u24_e32 v41, 0x540, v56
	s_waitcnt lgkmcnt(0)
	v_add_f32_e32 v29, v29, v40
	ds_bpermute_b32 v39, v39, v29
	s_waitcnt lgkmcnt(0)
; __device__ __forceinline__ float frcp(float x) { return __builtin_amdgcn_rcpf(x); }
; __device__ void swa_item(const Params& p, int item) {
;     ...
;   _Pragma("unroll") for (int ci = 0; ci < 9; ++ci) _Pragma("unroll") for (int jj = 0; jj < 4; ++jj) Pl[(q * 4 + jj) * 168 + ci * 16 + c] = f2bf(S[ci][jj]);
;   _Pragma("unroll") for (int jj = 0; jj < 4; ++jj) Pl[(q * 4 + jj) * 168 + 144 + c] = 0;
;   asm volatile("s_waitcnt lgkmcnt(0)" ::: "memory");
;   bf16x8 pf[5];
;   _Pragma("unroll") for (int kk = 0; kk < 5; ++kk) pf[kk] = *(const bf16x8*)(Pl + c * 168 + kk * 32 + q * 8);
;   asm volatile("s_waitcnt lgkmcnt(0)" ::: "memory");
;   float il[4];
;   _Pragma("unroll") for (int jj = 0; jj < 4; ++jj) il[jj] = frcp(ls[jj]);
;   bfu* Ow = Pl;
;   _Pragma("unroll") for (int dt = 0; dt < 8; ++dt) {
;     f32x4 a = (f32x4){0.f, 0.f, 0.f, 0.f};
;     _Pragma("unroll") for (int kk = 0; kk < 5; ++kk) {
;       const int k0_ = w * 16 + kk * 32 + q * 8; const int ch_ = k0_ >> 3;
;       const int chp_ = (ch_ < 32) ? (ch_ ^ (((dt * 16 + c) >> 3) & 15)) : ch_;
;       bf16x8 vf = *(const bf16x8*)(Vt + (dt * 16 + c) * 280 + chp_ * 8);
;       a = __builtin_amdgcn_mfma_f32_16x16x32_bf16(pf[kk], vf, a, 0, 0, 0);
;     }
	v_add_f32_e32 v29, v29, v39
	v_lshlrev_b32_e32 v39, 1, v55
	v_add_u32_e32 v40, v57, v39
	v_mad_u32_u24 v42, v56, s0, v40
	ds_write_b16_d16_hi v42, v2
	v_bfe_u32 v2, v3, 16, 1
	s_movk_i32 s0, 0x150
	v_add3_u32 v2, v3, v2, s72
	v_mad_u32_u24 v59, v43, s0, v40
	ds_write_b16_d16_hi v59, v2
	v_bfe_u32 v2, v4, 16, 1
	v_add3_u32 v2, v4, v2, s72
	v_mad_u32_u24 v4, v43, s0, s0
	v_add_u32_e32 v60, v40, v4
	ds_write_b16_d16_hi v60, v2
	v_bfe_u32 v2, v5, 16, 1
	v_add3_u32 v2, v5, v2, s72
	v_mov_b32_e32 v5, 0x2a0
	v_mad_u32_u24 v5, v43, s0, v5
	v_add_u32_e32 v61, v40, v5
	ds_write_b16_d16_hi v61, v2
	v_bfe_u32 v2, v10, 16, 1
	v_add3_u32 v2, v10, v2, s72
	ds_write_b16_d16_hi v42, v2 offset:32
	v_bfe_u32 v2, v11, 16, 1
	v_add3_u32 v2, v11, v2, s72
	ds_write_b16_d16_hi v59, v2 offset:32
	v_bfe_u32 v2, v8, 16, 1
	v_add3_u32 v2, v8, v2, s72
	ds_write_b16_d16_hi v60, v2 offset:32
	v_bfe_u32 v2, v9, 16, 1
	v_add3_u32 v2, v9, v2, s72
	ds_write_b16_d16_hi v61, v2 offset:32
	v_bfe_u32 v2, v6, 16, 1
	v_add3_u32 v2, v6, v2, s72
	ds_write_b16_d16_hi v42, v2 offset:64
	v_bfe_u32 v2, v7, 16, 1
	v_add3_u32 v2, v7, v2, s72
	ds_write_b16_d16_hi v59, v2 offset:64
	v_bfe_u32 v2, v12, 16, 1
	v_add3_u32 v2, v12, v2, s72
	ds_write_b16_d16_hi v60, v2 offset:64
	v_bfe_u32 v2, v13, 16, 1
	v_add3_u32 v2, v13, v2, s72
	ds_write_b16_d16_hi v61, v2 offset:64
	v_bfe_u32 v2, v18, 16, 1
	v_add3_u32 v2, v18, v2, s72
	ds_write_b16_d16_hi v42, v2 offset:96
	v_bfe_u32 v2, v19, 16, 1
	v_add3_u32 v2, v19, v2, s72
	ds_write_b16_d16_hi v59, v2 offset:96
	v_bfe_u32 v2, v16, 16, 1
	v_add3_u32 v2, v16, v2, s72
	ds_write_b16_d16_hi v60, v2 offset:96
	v_bfe_u32 v2, v17, 16, 1
	v_add3_u32 v2, v17, v2, s72
	ds_write_b16_d16_hi v61, v2 offset:96
	v_bfe_u32 v2, v14, 16, 1
	v_add3_u32 v2, v14, v2, s72
	ds_write_b16_d16_hi v42, v2 offset:128
	v_bfe_u32 v2, v15, 16, 1
	v_add3_u32 v2, v15, v2, s72
	ds_write_b16_d16_hi v59, v2 offset:128
	v_bfe_u32 v2, v32, 16, 1
	v_add3_u32 v2, v32, v2, s72
	ds_write_b16_d16_hi v60, v2 offset:128
	v_bfe_u32 v2, v21, 16, 1
	v_add3_u32 v2, v21, v2, s72
	ds_write_b16_d16_hi v61, v2 offset:128
	v_bfe_u32 v2, v34, 16, 1
	v_add3_u32 v2, v34, v2, s72
	ds_write_b16_d16_hi v42, v2 offset:160
	v_bfe_u32 v2, v46, 16, 1
	v_add3_u32 v2, v46, v2, s72
	ds_write_b16_d16_hi v59, v2 offset:160
	v_bfe_u32 v2, v49, 16, 1
	v_add3_u32 v2, v49, v2, s72
	ds_write_b16_d16_hi v60, v2 offset:160
	v_bfe_u32 v2, v53, 16, 1
	v_add3_u32 v2, v53, v2, s72
	ds_write_b16_d16_hi v61, v2 offset:160
	v_bfe_u32 v2, v30, 16, 1
	v_add3_u32 v2, v30, v2, s72
	ds_write_b16_d16_hi v42, v2 offset:192
	v_bfe_u32 v2, v31, 16, 1
	v_add3_u32 v2, v31, v2, s72
	ds_write_b16_d16_hi v59, v2 offset:192
	v_bfe_u32 v2, v48, 16, 1
	v_add3_u32 v2, v48, v2, s72
	ds_write_b16_d16_hi v60, v2 offset:192
	v_bfe_u32 v2, v54, 16, 1
	v_add3_u32 v2, v54, v2, s72
	ds_write_b16_d16_hi v61, v2 offset:192
	v_bfe_u32 v2, v45, 16, 1
	v_add3_u32 v2, v45, v2, s72
	ds_write_b16_d16_hi v42, v2 offset:224
	v_bfe_u32 v2, v47, 16, 1
	v_add3_u32 v2, v47, v2, s72
	ds_write_b16_d16_hi v59, v2 offset:224
	v_bfe_u32 v2, v36, 16, 1
	v_add3_u32 v2, v36, v2, s72
	ds_write_b16_d16_hi v60, v2 offset:224
	v_bfe_u32 v2, v33, 16, 1
	v_add3_u32 v2, v33, v2, s72
	ds_write_b16_d16_hi v61, v2 offset:224
	v_bfe_u32 v2, v44, 16, 1
	v_add3_u32 v2, v44, v2, s72
	ds_write_b16_d16_hi v42, v2 offset:256
	v_bfe_u32 v2, v35, 16, 1
	v_add3_u32 v2, v35, v2, s72
	ds_write_b16_d16_hi v59, v2 offset:256
	v_bfe_u32 v2, v20, 16, 1
	v_add3_u32 v2, v20, v2, s72
	ds_write_b16_d16_hi v60, v2 offset:256
	v_bfe_u32 v2, v37, 16, 1
	v_add3_u32 v2, v37, v2, s72
	v_mul_u32_u24_e32 v3, 0x150, v43
	ds_write_b16_d16_hi v61, v2 offset:256
	v_add3_u32 v2, v57, v41, v39
	ds_write_b16 v2, v1 offset:288
	v_add3_u32 v2, v57, v3, v39
	ds_write_b16 v2, v1 offset:288
	v_add3_u32 v2, v57, v4, v39
	v_lshl_add_u32 v45, v56, 3, v58
	s_movk_i32 s0, 0x100
	ds_write_b16 v2, v1 offset:288
	v_add3_u32 v2, v57, v5, v39
	v_and_b32_e32 v46, 8, v50
	v_cmp_gt_i32_e32 vcc, s0, v45
	ds_write_b16 v2, v1 offset:288
	v_mul_u32_u24_e32 v2, 0x150, v55
	v_cndmask_b32_e32 v30, 0, v46, vcc
	s_waitcnt lgkmcnt(0)
	v_add3_u32 v2, v57, v2, v52
	v_mad_u32_u24 v47, v55, s25, 0
	v_xor_b32_e32 v30, v30, v45
	ds_read_b128 v[18:21], v2
	ds_read_b128 v[14:17], v2 offset:64
	ds_read_b128 v[10:13], v2 offset:128
	ds_read_b128 v[6:9], v2 offset:192
	ds_read_b128 v[2:5], v2 offset:256
	s_waitcnt lgkmcnt(0)
	v_lshl_add_u32 v30, v30, 1, v47
	s_movk_i32 s0, 0xe0
	ds_read_b128 v[30:33], v30
	v_cmp_gt_i32_e64 s[0:1], s0, v45
	v_add_u32_e32 v48, 32, v45
	v_cmp_gt_i32_e64 s[38:39], s2, v45
	v_cndmask_b32_e64 v34, 0, v46, s[0:1]
	v_xor_b32_e32 v34, v34, v48
	v_lshl_add_u32 v34, v34, 1, v47
	ds_read_b128 v[34:37], v34
	s_waitcnt lgkmcnt(1)
	v_mfma_f32_16x16x32_bf16 v[30:33], v[18:21], v[30:33], 0
	v_add_u32_e32 v49, 64, v45
	s_movk_i32 s2, 0xa0
	v_cmp_gt_i32_e64 s[40:41], s2, v45
	s_waitcnt lgkmcnt(0)
	v_mfma_f32_16x16x32_bf16 v[30:33], v[14:17], v[34:37], v[30:33]
	v_cndmask_b32_e64 v34, 0, v46, s[38:39]
	v_xor_b32_e32 v34, v34, v49
	v_lshl_add_u32 v34, v34, 1, v47
	ds_read_b128 v[34:37], v34
	v_add_u32_e32 v50, 0x60, v45
	s_waitcnt lgkmcnt(0)
	v_mfma_f32_16x16x32_bf16 v[30:33], v[10:13], v[34:37], v[30:33]
	v_cndmask_b32_e64 v34, 0, v46, s[40:41]
	v_xor_b32_e32 v34, v34, v50
	v_lshl_add_u32 v34, v34, 1, v47
	ds_read_b128 v[34:37], v34
	s_movk_i32 s2, 0x80
	v_cmp_gt_i32_e64 s[42:43], s2, v45
	s_waitcnt lgkmcnt(0)
	v_mfma_f32_16x16x32_bf16 v[30:33], v[6:9], v[34:37], v[30:33]
	v_add_u32_e32 v52, 0x80, v45
	v_cndmask_b32_e64 v34, 0, v46, s[42:43]
	v_xor_b32_e32 v34, v34, v52
	v_lshl_add_u32 v34, v34, 1, v47
	ds_read_b128 v[34:37], v34
	v_rcp_f32_e32 v39, v26
	s_waitcnt lgkmcnt(0)
; __device__ __forceinline__ float frcp(float x) { return __builtin_amdgcn_rcpf(x); }
; __device__ void swa_item(const Params& p, int item) {
;     ...
;   _Pragma("unroll") for (int jj = 0; jj < 4; ++jj) il[jj] = frcp(ls[jj]);
;   bfu* Ow = Pl;
;   _Pragma("unroll") for (int dt = 0; dt < 8; ++dt) {
;     f32x4 a = (f32x4){0.f, 0.f, 0.f, 0.f};
;     _Pragma("unroll") for (int kk = 0; kk < 5; ++kk) {
;       const int k0_ = w * 16 + kk * 32 + q * 8; const int ch_ = k0_ >> 3;
;       const int chp_ = (ch_ < 32) ? (ch_ ^ (((dt * 16 + c) >> 3) & 15)) : ch_;
;       bf16x8 vf = *(const bf16x8*)(Vt + (dt * 16 + c) * 280 + chp_ * 8);
;       a = __builtin_amdgcn_mfma_f32_16x16x32_bf16(pf[kk], vf, a, 0, 0, 0);
;     }
;     _Pragma("unroll") for (int jj = 0; jj < 4; ++jj) Ow[(q * 4 + jj) * 136 + dt * 16 + c] = f2bf(a[jj] * il[jj]);
;   }
	v_mfma_f32_16x16x32_bf16 v[30:33], v[2:5], v[34:37], v[30:33]
	v_rcp_f32_e32 v41, v27
	s_movk_i32 s2, 0x440
	v_rcp_f32_e32 v42, v28
	s_nop 4
	v_mul_f32_e32 v30, v39, v30
	v_bfe_u32 v34, v30, 16, 1
	v_add3_u32 v30, v30, v34, s72
	v_mad_u32_u24 v53, v56, s2, v40
	ds_write_b16_d16_hi v53, v30
	v_mul_f32_e32 v30, v41, v31
	v_bfe_u32 v31, v30, 16, 1
	v_rcp_f32_e32 v44, v29
	v_add3_u32 v30, v30, v31, s72
	v_mad_u32_u24 v40, v43, s3, v40
	ds_write_b16_d16_hi v40, v30
	v_mul_f32_e32 v30, v42, v32
	v_bfe_u32 v31, v30, 16, 1
	v_add3_u32 v30, v30, v31, s72
	ds_write_b16_d16_hi v40, v30 offset:272
	v_mul_f32_e32 v30, v44, v33
	v_bfe_u32 v31, v30, 16, 1
	v_add3_u32 v30, v30, v31, s72
	v_or_b32_e32 v43, 16, v46
	ds_write_b16_d16_hi v40, v30 offset:544
	v_cndmask_b32_e32 v30, 0, v43, vcc
	v_xor_b32_e32 v30, v30, v45
	v_lshl_add_u32 v30, v30, 1, v47
	ds_read_b128 v[30:33], v30 offset:8960
	v_cndmask_b32_e64 v34, 0, v43, s[0:1]
	v_xor_b32_e32 v34, v34, v48
	v_lshl_add_u32 v34, v34, 1, v47
	ds_read_b128 v[34:37], v34 offset:8960
	s_waitcnt lgkmcnt(1)
	v_mfma_f32_16x16x32_bf16 v[30:33], v[18:21], v[30:33], 0
	s_waitcnt lgkmcnt(0)
	v_mfma_f32_16x16x32_bf16 v[30:33], v[14:17], v[34:37], v[30:33]
	v_cndmask_b32_e64 v34, 0, v43, s[38:39]
	v_xor_b32_e32 v34, v34, v49
	v_lshl_add_u32 v34, v34, 1, v47
	ds_read_b128 v[34:37], v34 offset:8960
	s_waitcnt lgkmcnt(0)
	v_mfma_f32_16x16x32_bf16 v[30:33], v[10:13], v[34:37], v[30:33]
	v_cndmask_b32_e64 v34, 0, v43, s[40:41]
	v_xor_b32_e32 v34, v34, v50
	v_lshl_add_u32 v34, v34, 1, v47
	ds_read_b128 v[34:37], v34 offset:8960
	s_waitcnt lgkmcnt(0)
	v_mfma_f32_16x16x32_bf16 v[30:33], v[6:9], v[34:37], v[30:33]
	v_cndmask_b32_e64 v34, 0, v43, s[42:43]
	v_xor_b32_e32 v34, v34, v52
	v_lshl_add_u32 v34, v34, 1, v47
	ds_read_b128 v[34:37], v34 offset:8960
	v_or_b32_e32 v43, 32, v46
	s_waitcnt lgkmcnt(0)
	v_mfma_f32_16x16x32_bf16 v[30:33], v[2:5], v[34:37], v[30:33]
	s_nop 7
	v_mul_f32_e32 v30, v39, v30
	v_bfe_u32 v34, v30, 16, 1
	v_add3_u32 v30, v30, v34, s72
	ds_write_b16_d16_hi v53, v30 offset:32
	v_mul_f32_e32 v30, v41, v31
	v_bfe_u32 v31, v30, 16, 1
	v_add3_u32 v30, v30, v31, s72
	ds_write_b16_d16_hi v40, v30 offset:32
	v_mul_f32_e32 v30, v42, v32
	v_bfe_u32 v31, v30, 16, 1
	v_add3_u32 v30, v30, v31, s72
	ds_write_b16_d16_hi v40, v30 offset:304
	v_mul_f32_e32 v30, v44, v33
	v_bfe_u32 v31, v30, 16, 1
	v_add3_u32 v30, v30, v31, s72
	ds_write_b16_d16_hi v40, v30 offset:576
	v_cndmask_b32_e32 v30, 0, v43, vcc
	v_xor_b32_e32 v30, v30, v45
	v_lshl_add_u32 v30, v30, 1, v47
	ds_read_b128 v[30:33], v30 offset:17920
	v_cndmask_b32_e64 v34, 0, v43, s[0:1]
	v_xor_b32_e32 v34, v34, v48
	v_lshl_add_u32 v34, v34, 1, v47
	ds_read_b128 v[34:37], v34 offset:17920
	s_waitcnt lgkmcnt(1)
	v_mfma_f32_16x16x32_bf16 v[30:33], v[18:21], v[30:33], 0
	s_waitcnt lgkmcnt(0)
	v_mfma_f32_16x16x32_bf16 v[30:33], v[14:17], v[34:37], v[30:33]
	v_cndmask_b32_e64 v34, 0, v43, s[38:39]
	v_xor_b32_e32 v34, v34, v49
	v_lshl_add_u32 v34, v34, 1, v47
	ds_read_b128 v[34:37], v34 offset:17920
	s_waitcnt lgkmcnt(0)
	v_mfma_f32_16x16x32_bf16 v[30:33], v[10:13], v[34:37], v[30:33]
	v_cndmask_b32_e64 v34, 0, v43, s[40:41]
	v_xor_b32_e32 v34, v34, v50
	v_lshl_add_u32 v34, v34, 1, v47
	ds_read_b128 v[34:37], v34 offset:17920
	s_waitcnt lgkmcnt(0)
	v_mfma_f32_16x16x32_bf16 v[30:33], v[6:9], v[34:37], v[30:33]
	v_cndmask_b32_e64 v34, 0, v43, s[42:43]
	v_xor_b32_e32 v34, v34, v52
	v_lshl_add_u32 v34, v34, 1, v47
	ds_read_b128 v[34:37], v34 offset:17920
	v_or_b32_e32 v43, 48, v46
	s_waitcnt lgkmcnt(0)
	v_mfma_f32_16x16x32_bf16 v[30:33], v[2:5], v[34:37], v[30:33]
	s_nop 7
	v_mul_f32_e32 v30, v39, v30
	v_bfe_u32 v34, v30, 16, 1
	v_add3_u32 v30, v30, v34, s72
	ds_write_b16_d16_hi v53, v30 offset:64
	v_mul_f32_e32 v30, v41, v31
	v_bfe_u32 v31, v30, 16, 1
	v_add3_u32 v30, v30, v31, s72
	ds_write_b16_d16_hi v40, v30 offset:64
	v_mul_f32_e32 v30, v42, v32
	v_bfe_u32 v31, v30, 16, 1
	v_add3_u32 v30, v30, v31, s72
	ds_write_b16_d16_hi v40, v30 offset:336
	v_mul_f32_e32 v30, v44, v33
	v_bfe_u32 v31, v30, 16, 1
	v_add3_u32 v30, v30, v31, s72
	ds_write_b16_d16_hi v40, v30 offset:608
	v_cndmask_b32_e32 v30, 0, v43, vcc
	v_xor_b32_e32 v30, v30, v45
	v_lshl_add_u32 v30, v30, 1, v47
	ds_read_b128 v[30:33], v30 offset:26880
	v_cndmask_b32_e64 v34, 0, v43, s[0:1]
	v_xor_b32_e32 v34, v34, v48
	v_lshl_add_u32 v34, v34, 1, v47
	ds_read_b128 v[34:37], v34 offset:26880
	s_waitcnt lgkmcnt(1)
	v_mfma_f32_16x16x32_bf16 v[30:33], v[18:21], v[30:33], 0
	s_waitcnt lgkmcnt(0)
	v_mfma_f32_16x16x32_bf16 v[30:33], v[14:17], v[34:37], v[30:33]
	v_cndmask_b32_e64 v34, 0, v43, s[38:39]
	v_xor_b32_e32 v34, v34, v49
	v_lshl_add_u32 v34, v34, 1, v47
	ds_read_b128 v[34:37], v34 offset:26880
	s_waitcnt lgkmcnt(0)
	v_mfma_f32_16x16x32_bf16 v[30:33], v[10:13], v[34:37], v[30:33]
	v_cndmask_b32_e64 v34, 0, v43, s[40:41]
	v_xor_b32_e32 v34, v34, v50
	v_lshl_add_u32 v34, v34, 1, v47
	ds_read_b128 v[34:37], v34 offset:26880
	s_waitcnt lgkmcnt(0)
	v_mfma_f32_16x16x32_bf16 v[30:33], v[6:9], v[34:37], v[30:33]
	v_cndmask_b32_e64 v34, 0, v43, s[42:43]
	v_xor_b32_e32 v34, v34, v52
	v_lshl_add_u32 v34, v34, 1, v47
	ds_read_b128 v[34:37], v34 offset:26880
	v_or_b32_e32 v43, 64, v46
	s_waitcnt lgkmcnt(0)
; __device__ void swa_item(const Params& p, int item) {
;     ...
;   _Pragma("unroll") for (int dt = 0; dt < 8; ++dt) {
;     f32x4 a = (f32x4){0.f, 0.f, 0.f, 0.f};
;     _Pragma("unroll") for (int kk = 0; kk < 5; ++kk) {
;       const int k0_ = w * 16 + kk * 32 + q * 8; const int ch_ = k0_ >> 3;
;       const int chp_ = (ch_ < 32) ? (ch_ ^ (((dt * 16 + c) >> 3) & 15)) : ch_;
;       bf16x8 vf = *(const bf16x8*)(Vt + (dt * 16 + c) * 280 + chp_ * 8);
;       a = __builtin_amdgcn_mfma_f32_16x16x32_bf16(pf[kk], vf, a, 0, 0, 0);
;     }
;     _Pragma("unroll") for (int jj = 0; jj < 4; ++jj) Ow[(q * 4 + jj) * 136 + dt * 16 + c] = f2bf(a[jj] * il[jj]);
;   }
	v_mfma_f32_16x16x32_bf16 v[30:33], v[2:5], v[34:37], v[30:33]
	s_nop 7
	v_mul_f32_e32 v30, v39, v30
	v_bfe_u32 v34, v30, 16, 1
	v_add3_u32 v30, v30, v34, s72
	ds_write_b16_d16_hi v53, v30 offset:96
	v_mul_f32_e32 v30, v41, v31
	v_bfe_u32 v31, v30, 16, 1
	v_add3_u32 v30, v30, v31, s72
	ds_write_b16_d16_hi v40, v30 offset:96
	v_mul_f32_e32 v30, v42, v32
	v_bfe_u32 v31, v30, 16, 1
	v_add3_u32 v30, v30, v31, s72
	ds_write_b16_d16_hi v40, v30 offset:368
	v_mul_f32_e32 v30, v44, v33
	v_bfe_u32 v31, v30, 16, 1
	v_add3_u32 v30, v30, v31, s72
	ds_write_b16_d16_hi v40, v30 offset:640
	v_cndmask_b32_e32 v30, 0, v43, vcc
	v_xor_b32_e32 v30, v30, v45
	v_lshl_add_u32 v30, v30, 1, v47
	ds_read_b128 v[30:33], v30 offset:35840
	v_cndmask_b32_e64 v34, 0, v43, s[0:1]
	v_xor_b32_e32 v34, v34, v48
	v_lshl_add_u32 v34, v34, 1, v47
	ds_read_b128 v[34:37], v34 offset:35840
	s_waitcnt lgkmcnt(1)
	v_mfma_f32_16x16x32_bf16 v[30:33], v[18:21], v[30:33], 0
	s_waitcnt lgkmcnt(0)
	v_mfma_f32_16x16x32_bf16 v[30:33], v[14:17], v[34:37], v[30:33]
	v_cndmask_b32_e64 v34, 0, v43, s[38:39]
	v_xor_b32_e32 v34, v34, v49
	v_lshl_add_u32 v34, v34, 1, v47
	ds_read_b128 v[34:37], v34 offset:35840
	s_waitcnt lgkmcnt(0)
	v_mfma_f32_16x16x32_bf16 v[30:33], v[10:13], v[34:37], v[30:33]
	v_cndmask_b32_e64 v34, 0, v43, s[40:41]
	v_xor_b32_e32 v34, v34, v50
	v_lshl_add_u32 v34, v34, 1, v47
	ds_read_b128 v[34:37], v34 offset:35840
	s_waitcnt lgkmcnt(0)
	v_mfma_f32_16x16x32_bf16 v[30:33], v[6:9], v[34:37], v[30:33]
	v_cndmask_b32_e64 v34, 0, v43, s[42:43]
	v_xor_b32_e32 v34, v34, v52
	v_lshl_add_u32 v34, v34, 1, v47
	ds_read_b128 v[34:37], v34 offset:35840
	v_or_b32_e32 v43, 0x50, v46
	s_waitcnt lgkmcnt(0)
	v_mfma_f32_16x16x32_bf16 v[30:33], v[2:5], v[34:37], v[30:33]
	s_nop 7
	v_mul_f32_e32 v30, v39, v30
	v_bfe_u32 v34, v30, 16, 1
	v_add3_u32 v30, v30, v34, s72
	ds_write_b16_d16_hi v53, v30 offset:128
	v_mul_f32_e32 v30, v41, v31
	v_bfe_u32 v31, v30, 16, 1
	v_add3_u32 v30, v30, v31, s72
	ds_write_b16_d16_hi v40, v30 offset:128
	v_mul_f32_e32 v30, v42, v32
	v_bfe_u32 v31, v30, 16, 1
	v_add3_u32 v30, v30, v31, s72
	ds_write_b16_d16_hi v40, v30 offset:400
	v_mul_f32_e32 v30, v44, v33
	v_bfe_u32 v31, v30, 16, 1
	v_add3_u32 v30, v30, v31, s72
	ds_write_b16_d16_hi v40, v30 offset:672
	v_cndmask_b32_e32 v30, 0, v43, vcc
	v_xor_b32_e32 v30, v30, v45
	v_lshl_add_u32 v30, v30, 1, v47
	ds_read_b128 v[30:33], v30 offset:44800
	v_cndmask_b32_e64 v34, 0, v43, s[0:1]
	v_xor_b32_e32 v34, v34, v48
	v_lshl_add_u32 v34, v34, 1, v47
	ds_read_b128 v[34:37], v34 offset:44800
	s_waitcnt lgkmcnt(1)
	v_mfma_f32_16x16x32_bf16 v[30:33], v[18:21], v[30:33], 0
	s_waitcnt lgkmcnt(0)
	v_mfma_f32_16x16x32_bf16 v[30:33], v[14:17], v[34:37], v[30:33]
	v_cndmask_b32_e64 v34, 0, v43, s[38:39]
	v_xor_b32_e32 v34, v34, v49
	v_lshl_add_u32 v34, v34, 1, v47
	ds_read_b128 v[34:37], v34 offset:44800
	s_waitcnt lgkmcnt(0)
	v_mfma_f32_16x16x32_bf16 v[30:33], v[10:13], v[34:37], v[30:33]
	v_cndmask_b32_e64 v34, 0, v43, s[40:41]
	v_xor_b32_e32 v34, v34, v50
	v_lshl_add_u32 v34, v34, 1, v47
	ds_read_b128 v[34:37], v34 offset:44800
	s_waitcnt lgkmcnt(0)
	v_mfma_f32_16x16x32_bf16 v[30:33], v[6:9], v[34:37], v[30:33]
	v_cndmask_b32_e64 v34, 0, v43, s[42:43]
	v_xor_b32_e32 v34, v34, v52
	v_lshl_add_u32 v34, v34, 1, v47
	ds_read_b128 v[34:37], v34 offset:44800
	v_or_b32_e32 v43, 0x60, v46
	s_waitcnt lgkmcnt(0)
	v_mfma_f32_16x16x32_bf16 v[30:33], v[2:5], v[34:37], v[30:33]
	s_nop 7
	v_mul_f32_e32 v30, v39, v30
	v_bfe_u32 v34, v30, 16, 1
	v_add3_u32 v30, v30, v34, s72
	ds_write_b16_d16_hi v53, v30 offset:160
	v_mul_f32_e32 v30, v41, v31
	v_bfe_u32 v31, v30, 16, 1
	v_add3_u32 v30, v30, v31, s72
	ds_write_b16_d16_hi v40, v30 offset:160
	v_mul_f32_e32 v30, v42, v32
	v_bfe_u32 v31, v30, 16, 1
	v_add3_u32 v30, v30, v31, s72
	ds_write_b16_d16_hi v40, v30 offset:432
	v_mul_f32_e32 v30, v44, v33
	v_bfe_u32 v31, v30, 16, 1
	v_add3_u32 v30, v30, v31, s72
	ds_write_b16_d16_hi v40, v30 offset:704
	v_cndmask_b32_e32 v30, 0, v43, vcc
	v_xor_b32_e32 v30, v30, v45
	v_lshl_add_u32 v30, v30, 1, v47
	ds_read_b128 v[30:33], v30 offset:53760
	v_cndmask_b32_e64 v34, 0, v43, s[0:1]
	v_xor_b32_e32 v34, v34, v48
	v_lshl_add_u32 v34, v34, 1, v47
	ds_read_b128 v[34:37], v34 offset:53760
	s_waitcnt lgkmcnt(1)
	v_mfma_f32_16x16x32_bf16 v[30:33], v[18:21], v[30:33], 0
	s_waitcnt lgkmcnt(0)
	v_mfma_f32_16x16x32_bf16 v[30:33], v[14:17], v[34:37], v[30:33]
	v_cndmask_b32_e64 v34, 0, v43, s[38:39]
	v_xor_b32_e32 v34, v34, v49
	v_lshl_add_u32 v34, v34, 1, v47
	ds_read_b128 v[34:37], v34 offset:53760
	s_waitcnt lgkmcnt(0)
	v_mfma_f32_16x16x32_bf16 v[30:33], v[10:13], v[34:37], v[30:33]
	v_cndmask_b32_e64 v34, 0, v43, s[40:41]
	v_xor_b32_e32 v34, v34, v50
	v_lshl_add_u32 v34, v34, 1, v47
	ds_read_b128 v[34:37], v34 offset:53760
	s_waitcnt lgkmcnt(0)
	v_mfma_f32_16x16x32_bf16 v[30:33], v[6:9], v[34:37], v[30:33]
	v_cndmask_b32_e64 v34, 0, v43, s[42:43]
	v_xor_b32_e32 v34, v34, v52
	v_lshl_add_u32 v34, v34, 1, v47
	ds_read_b128 v[34:37], v34 offset:53760
	s_waitcnt lgkmcnt(0)
; __device__ __forceinline__ float flog(float x) { return __builtin_amdgcn_logf(x) * 0.6931471805599453f; }
; __device__ void swa_item(const Params& p, int item) {
;     ...
;     _Pragma("unroll") for (int jj = 0; jj < 4; ++jj) Ow[(q * 4 + jj) * 136 + dt * 16 + c] = f2bf(a[jj] * il[jj]);
;   }
;   asm volatile("s_waitcnt lgkmcnt(0)" ::: "memory");
;   _Pragma("unroll") for (int i = 0; i < 4; ++i) {
;     const int id = lane + 64 * i; const int rr = id >> 4, c8 = id & 15;
;     long orow = rowb + (long)(qb * 128 + w * 16 + rr) * dil + r;
;     *(bf16x8*)(buf + orow * 4608 + qcol + c8 * 8) = *(const bf16x8*)(Ow + rr * 136 + c8 * 8);
;   }
;   if (c == 0) {
;     _Pragma("unroll") for (int jj = 0; jj < 4; ++jj) {
;       long orow = rowb + (long)(qb * 128 + w * 16 + q * 4 + jj) * dil + r;
;       misc[MF_LSE + ((long)pat * MTOK + orow) * 4 + head] = mx[jj] + flog(ls[jj]);
;     }
;   }
	v_mfma_f32_16x16x32_bf16 v[30:33], v[2:5], v[34:37], v[30:33]
	s_nop 7
	v_mul_f32_e32 v30, v39, v30
	v_bfe_u32 v34, v30, 16, 1
	v_add3_u32 v30, v30, v34, s72
	ds_write_b16_d16_hi v53, v30 offset:192
	v_mul_f32_e32 v30, v41, v31
	v_bfe_u32 v31, v30, 16, 1
	v_add3_u32 v30, v30, v31, s72
	ds_write_b16_d16_hi v40, v30 offset:192
	v_mul_f32_e32 v30, v42, v32
	v_bfe_u32 v31, v30, 16, 1
	v_add3_u32 v30, v30, v31, s72
	ds_write_b16_d16_hi v40, v30 offset:464
	v_mul_f32_e32 v30, v44, v33
	v_bfe_u32 v31, v30, 16, 1
	v_add3_u32 v30, v30, v31, s72
	v_or_b32_e32 v34, 0x70, v46
	ds_write_b16_d16_hi v40, v30 offset:736
	v_cndmask_b32_e32 v30, 0, v34, vcc
	v_xor_b32_e32 v30, v30, v45
	v_lshl_add_u32 v30, v30, 1, v47
	ds_read_b128 v[30:33], v30 offset:62720
	v_cmp_eq_u32_e32 vcc, 0, v55
	s_waitcnt lgkmcnt(0)
	v_mfma_f32_16x16x32_bf16 v[18:21], v[18:21], v[30:33], 0
	v_cndmask_b32_e64 v30, 0, v34, s[0:1]
	v_xor_b32_e32 v30, v30, v48
	v_lshl_add_u32 v30, v30, 1, v47
	ds_read_b128 v[30:33], v30 offset:62720
	s_waitcnt lgkmcnt(0)
	v_mfma_f32_16x16x32_bf16 v[14:17], v[14:17], v[30:33], v[18:21]
	s_nop 2
	v_cndmask_b32_e64 v18, 0, v34, s[38:39]
	v_xor_b32_e32 v18, v18, v49
	v_lshl_add_u32 v18, v18, 1, v47
	ds_read_b128 v[18:21], v18 offset:62720
	s_waitcnt lgkmcnt(0)
	v_mfma_f32_16x16x32_bf16 v[10:13], v[10:13], v[18:21], v[14:17]
	s_nop 2
	v_cndmask_b32_e64 v14, 0, v34, s[40:41]
	v_xor_b32_e32 v14, v14, v50
	v_lshl_add_u32 v14, v14, 1, v47
	ds_read_b128 v[14:17], v14 offset:62720
	s_waitcnt lgkmcnt(0)
	v_mfma_f32_16x16x32_bf16 v[6:9], v[6:9], v[14:17], v[10:13]
	s_nop 2
	v_cndmask_b32_e64 v10, 0, v34, s[42:43]
	v_xor_b32_e32 v10, v10, v52
	v_lshl_add_u32 v10, v10, 1, v47
	ds_read_b128 v[10:13], v10 offset:62720
	s_waitcnt lgkmcnt(0)
	v_mfma_f32_16x16x32_bf16 v[2:5], v[2:5], v[10:13], v[6:9]
	s_nop 2
	v_or_b32_e32 v8, v51, v56
	v_ashrrev_i32_e32 v9, 31, v8
	s_nop 2
	v_mul_f32_e32 v2, v39, v2
	v_bfe_u32 v6, v2, 16, 1
	v_add3_u32 v2, v2, v6, s72
	ds_write_b16_d16_hi v53, v2 offset:224
	v_mul_f32_e32 v2, v41, v3
	v_bfe_u32 v3, v2, 16, 1
	v_add3_u32 v2, v2, v3, s72
	ds_write_b16_d16_hi v40, v2 offset:224
	v_mul_f32_e32 v2, v42, v4
	v_bfe_u32 v3, v2, 16, 1
	v_add3_u32 v2, v2, v3, s72
	ds_write_b16_d16_hi v40, v2 offset:496
	v_mul_f32_e32 v2, v44, v5
	v_bfe_u32 v3, v2, 16, 1
	v_add3_u32 v2, v2, v3, s72
	ds_write_b16_d16_hi v40, v2 offset:768
	v_lshlrev_b64 v[2:3], s22, v[8:9]
	v_lshl_add_u64 v[10:11], v[2:3], 0, s[26:27]
	v_mul_u32_u24_e32 v2, 0x110, v56
	s_waitcnt lgkmcnt(0)
	v_lshl_add_u64 v[6:7], s[52:53], 0, v[0:1]
	v_add3_u32 v0, v57, v0, v2
	ds_read_b128 v[2:5], v0
	v_mad_u64_u32 v[12:13], s[0:1], v10, s89, v[6:7]
	v_mad_i32_i24 v13, v11, s89, v13
	s_waitcnt lgkmcnt(0)
	global_store_dwordx4 v[12:13], v[2:5], off
	s_nop 1
	v_or_b32_e32 v2, 4, v8
	v_ashrrev_i32_e32 v3, 31, v2
	v_lshlrev_b64 v[2:3], s22, v[2:3]
	v_lshl_add_u64 v[10:11], v[2:3], 0, s[26:27]
	ds_read_b128 v[2:5], v0 offset:1088
	v_mad_u64_u32 v[12:13], s[0:1], v10, s89, v[6:7]
	v_mad_i32_i24 v13, v11, s89, v13
	s_waitcnt lgkmcnt(0)
	global_store_dwordx4 v[12:13], v[2:5], off
	s_nop 1
	v_or_b32_e32 v2, 8, v8
	v_ashrrev_i32_e32 v3, 31, v2
	v_lshlrev_b64 v[2:3], s22, v[2:3]
	v_lshl_add_u64 v[10:11], v[2:3], 0, s[26:27]
	ds_read_b128 v[2:5], v0 offset:2176
	v_mad_u64_u32 v[12:13], s[0:1], v10, s89, v[6:7]
	v_mad_i32_i24 v13, v11, s89, v13
	s_waitcnt lgkmcnt(0)
	global_store_dwordx4 v[12:13], v[2:5], off
	s_nop 1
	v_or_b32_e32 v2, 12, v8
	v_ashrrev_i32_e32 v3, 31, v2
	v_lshlrev_b64 v[2:3], s22, v[2:3]
	v_lshl_add_u64 v[8:9], v[2:3], 0, s[26:27]
	ds_read_b128 v[2:5], v0 offset:3264
	v_mad_u64_u32 v[6:7], s[0:1], v8, s89, v[6:7]
	v_mad_i32_i24 v7, v9, s89, v7
	s_waitcnt lgkmcnt(0)
	global_store_dwordx4 v[6:7], v[2:5], off
	s_and_saveexec_b64 s[0:1], vcc
	s_cbranch_execz .LBB0_101
	s_ashr_i32 s89, s88, 31
	s_lshl_b64 s[2:3], s[88:89], 19
	v_readlane_b32 s12, v252, 20
	v_log_f32_e32 v0, v26
	s_add_u32 s2, s12, s2
	v_readlane_b32 s12, v252, 21
	v_or_b32_e32 v2, v51, v38
	s_addc_u32 s3, s12, s3
	s_lshl_b32 s12, s23, 2
	s_add_u32 s2, s2, s12
	v_ashrrev_i32_e32 v3, 31, v2
	v_readlane_b32 s12, v254, 13
	v_lshlrev_b64 v[4:5], s22, v[2:3]
	v_readlane_b32 s13, v254, 14
	v_fmac_f32_e32 v22, 0x3f317218, v0
	v_log_f32_e32 v0, v27
	s_addc_u32 s3, s3, 0
	v_lshl_add_u64 v[4:5], v[4:5], 0, s[12:13]
	v_lshl_add_u64 v[4:5], v[4:5], 4, s[2:3]
	global_store_dword v[4:5], v22, off
	v_or_b32_e32 v4, 1, v2
	v_ashrrev_i32_e32 v5, 31, v4
	v_fmac_f32_e32 v23, 0x3f317218, v0
	v_log_f32_e32 v0, v28
	v_lshlrev_b64 v[4:5], s22, v[4:5]
	v_lshl_add_u64 v[4:5], v[4:5], 0, s[12:13]
	v_lshl_add_u64 v[4:5], v[4:5], 4, s[2:3]
	global_store_dword v[4:5], v23, off
	v_or_b32_e32 v4, 2, v2
	v_fmac_f32_e32 v24, 0x3f317218, v0
	v_or_b32_e32 v2, 3, v2
	v_log_f32_e32 v0, v29
	v_ashrrev_i32_e32 v5, 31, v4
	v_ashrrev_i32_e32 v3, 31, v2
	v_lshlrev_b64 v[4:5], s22, v[4:5]
	v_lshlrev_b64 v[2:3], s22, v[2:3]
	v_lshl_add_u64 v[4:5], v[4:5], 0, s[12:13]
	v_lshl_add_u64 v[2:3], v[2:3], 0, s[12:13]
	s_movk_i32 s89, 0x2400
	v_lshl_add_u64 v[4:5], v[4:5], 4, s[2:3]
	v_fmac_f32_e32 v25, 0x3f317218, v0
	v_lshl_add_u64 v[2:3], v[2:3], 4, s[2:3]
	global_store_dword v[4:5], v24, off
	global_store_dword v[2:3], v25, off
	s_branch .LBB0_101

; __device__ __forceinline__ float bf2f(bfu h) { return __uint_as_float(((unsigned)h) << 16); }
; __device__ __forceinline__ unsigned pack2(float a, float b) { return (unsigned)f2bf(a) | ((unsigned)f2bf(b) << 16); }
; __device__ __forceinline__ float fexp(float x) { return __builtin_amdgcn_exp2f(x * 1.4426950408889634f); }
; __device__ __forceinline__ float frcp(float x) { return __builtin_amdgcn_rcpf(x); }
; __device__ void cd_fin_rows(const Params& p, int L, int row0, int nrows, const bool doC, const bool doD) {
;     ...
;     if (doD) {
;     const int head = lane >> 4;
;     float l0 = misc[MF_LSE + ((long)0 * MTOK + row) * 4 + head];
;     float l1 = misc[MF_LSE + ((long)1 * MTOK + row) * 4 + head];
;     float l2 = misc[MF_LSE + ((long)2 * MTOK + row) * 4 + head];
;     float mm = fmaxf(l0, fmaxf(l1, l2));
;     float e0 = fexp(l0 - mm), e1 = fexp(l1 - mm), e2 = fexp(l2 - mm);
;     float inv = frcp(e0 + e1 + e2);
;     e0 *= inv; e1 *= inv; e2 *= inv;
;     bf16x8 o0 = *(const bf16x8*)(pr + c0), o1 = *(const bf16x8*)(pr + 512 + c0), o2 = *(const bf16x8*)(pr + 1024 + c0);
;     float rd[8];
;     for (int e = 0; e < 8; ++e) rd[e] = e0 * bf2f((bfu)o0[e]) + e1 * bf2f((bfu)o1[e]) + e2 * bf2f((bfu)o2[e]);
;     uint4 wb; wb.x = pack2(rd[0], rd[1]); wb.y = pack2(rd[2], rd[3]); wb.z = pack2(rd[4], rd[5]); wb.w = pack2(rd[6], rd[7]);
;     *(uint4*)(pr + c0) = wb;
.LBB0_351:
	s_mov_b64 s[0:1], -1
	s_and_b64 vcc, exec, s[56:57]
	s_cbranch_vccz .LBB0_356
	v_mbcnt_lo_u32_b32 v0, -1, 0
	v_mbcnt_hi_u32_b32 v0, -1, v0
	s_movk_i32 s0, 0x80
	v_or_b32_e32 v0, s33, v0
	s_waitcnt lgkmcnt(0)
	v_ashrrev_i32_e32 v2, 6, v0
	v_cmp_gt_i32_e32 vcc, s0, v2
	s_and_saveexec_b64 s[0:1], vcc
	s_mov_b64 s[14:15], 0x12000
	s_mov_b64 s[20:21], 0x80
	s_cbranch_execz .LBB0_355
	v_and_b32_e32 v7, 63, v0
	v_add_u32_e32 v4, s18, v2
	v_lshrrev_b32_e32 v6, 2, v7
	v_and_b32_e32 v6, 12, v6
	v_lshl_add_u32 v8, v4, 4, v6
	v_mov_b32_e32 v9, 0
	v_lshl_add_u64 v[8:9], s[10:11], 0, v[8:9]
	v_add_co_u32_e32 v8, vcc, 0x7533000, v8
	s_nop 1
	v_addc_co_u32_e32 v9, vcc, 0, v9, vcc
	s_mov_b64 s[2:3], 0x80000
	v_lshl_add_u64 v[10:11], v[8:9], 0, s[2:3]
	v_lshl_add_u64 v[12:13], v[10:11], 0, s[2:3]
	v_mad_u64_u32 v[14:15], vcc, v4, s89, 0
	v_lshlrev_b32_e32 v6, 4, v7
	v_mov_b32_e32 v7, 0
	v_lshl_add_u64 v[14:15], v[14:15], 0, v[6:7]
	v_lshl_add_u64 v[14:15], s[10:11], 0, v[14:15]
	v_add_co_u32_e32 v14, vcc, 0xc200000, v14
	s_nop 1
	v_addc_co_u32_e32 v15, vcc, 0, v15, vcc
	s_mov_b64 s[2:3], 0x12000
	v_lshl_add_u64 v[16:17], v[14:15], 0, s[2:3]
	v_lshl_add_u64 v[18:19], v[16:17], 0, s[2:3]
	v_lshl_add_u64 v[80:81], v[18:19], 0, s[2:3]
	s_mov_b64 s[2:3], 0x48000
	s_mov_b64 s[12:13], 0x200
	s_movk_i32 s14, 4
.Lfd_loop:
	global_load_dword v20, v[8:9], off
	global_load_dword v21, v[10:11], off
	global_load_dword v22, v[12:13], off
	global_load_dword v23, v[8:9], off offset:128
	global_load_dword v24, v[10:11], off offset:128
	global_load_dword v25, v[12:13], off offset:128
	global_load_dword v26, v[8:9], off offset:256
	global_load_dword v27, v[10:11], off offset:256
	global_load_dword v28, v[12:13], off offset:256
	global_load_dword v29, v[8:9], off offset:384
	global_load_dword v30, v[10:11], off offset:384
	global_load_dword v31, v[12:13], off offset:384
	global_load_dwordx4 v[32:35], v[14:15], off
	global_load_dwordx4 v[36:39], v[14:15], off offset:1024
	global_load_dwordx4 v[40:43], v[14:15], off offset:2048
	global_load_dwordx4 v[44:47], v[16:17], off
	global_load_dwordx4 v[48:51], v[16:17], off offset:1024
	global_load_dwordx4 v[52:55], v[16:17], off offset:2048
	global_load_dwordx4 v[56:59], v[18:19], off
	global_load_dwordx4 v[60:63], v[18:19], off offset:1024
	global_load_dwordx4 v[64:67], v[18:19], off offset:2048
	global_load_dwordx4 v[68:71], v[80:81], off
	global_load_dwordx4 v[72:75], v[80:81], off offset:1024
	global_load_dwordx4 v[76:79], v[80:81], off offset:2048
	s_waitcnt vmcnt(9)
	v_max3_f32 v82, v20, v21, v22
	v_sub_f32_e32 v20, v20, v82
	v_sub_f32_e32 v21, v21, v82
	v_sub_f32_e32 v22, v22, v82
	v_mul_f32_e32 v20, 0x3fb8aa3b, v20
	v_mul_f32_e32 v21, 0x3fb8aa3b, v21
	v_mul_f32_e32 v22, 0x3fb8aa3b, v22
	v_exp_f32_e32 v20, v20
	v_exp_f32_e32 v21, v21
	v_exp_f32_e32 v22, v22
	v_add_f32_e32 v83, v20, v21
	v_add_f32_e32 v83, v22, v83
	v_rcp_f32_e32 v83, v83
	v_lshlrev_b32_e32 v84, 16, v32
	v_and_b32_e32 v87, 0xffff0000, v32
	v_lshlrev_b32_e32 v85, 16, v36
	v_and_b32_e32 v88, 0xffff0000, v36
	v_lshlrev_b32_e32 v86, 16, v40
	v_and_b32_e32 v89, 0xffff0000, v40
	v_mul_f32_e32 v20, v20, v83
	v_mul_f32_e32 v21, v21, v83
	v_mul_f32_e32 v22, v22, v83
	v_mul_f32_e32 v90, v20, v84
	v_mul_f32_e32 v91, v20, v87
	v_fmac_f32_e32 v90, v21, v85
	v_fmac_f32_e32 v91, v21, v88
	v_fmac_f32_e32 v90, v22, v86
	v_fmac_f32_e32 v91, v22, v89
	v_cvt_pk_bf16_f32 v32, v90, v91
	v_lshlrev_b32_e32 v84, 16, v33
	v_and_b32_e32 v87, 0xffff0000, v33
	v_lshlrev_b32_e32 v85, 16, v37
	v_and_b32_e32 v88, 0xffff0000, v37
	v_lshlrev_b32_e32 v86, 16, v41
	v_and_b32_e32 v89, 0xffff0000, v41
	v_mul_f32_e32 v90, v20, v84
	v_mul_f32_e32 v91, v20, v87
	v_fmac_f32_e32 v90, v21, v85
	v_fmac_f32_e32 v91, v21, v88
	v_fmac_f32_e32 v90, v22, v86
	v_fmac_f32_e32 v91, v22, v89
	v_cvt_pk_bf16_f32 v33, v90, v91
	v_lshlrev_b32_e32 v84, 16, v34
	v_and_b32_e32 v87, 0xffff0000, v34
	v_lshlrev_b32_e32 v85, 16, v38
	v_and_b32_e32 v88, 0xffff0000, v38
	v_lshlrev_b32_e32 v86, 16, v42
	v_and_b32_e32 v89, 0xffff0000, v42
	v_mul_f32_e32 v90, v20, v84
	v_mul_f32_e32 v91, v20, v87
	v_fmac_f32_e32 v90, v21, v85
	v_fmac_f32_e32 v91, v21, v88
	v_fmac_f32_e32 v90, v22, v86
	v_fmac_f32_e32 v91, v22, v89
	v_cvt_pk_bf16_f32 v34, v90, v91
	v_lshlrev_b32_e32 v84, 16, v35
	v_and_b32_e32 v87, 0xffff0000, v35
	v_lshlrev_b32_e32 v85, 16, v39
	v_and_b32_e32 v88, 0xffff0000, v39
	v_lshlrev_b32_e32 v86, 16, v43
	v_and_b32_e32 v89, 0xffff0000, v43
	v_mul_f32_e32 v90, v20, v84
	v_mul_f32_e32 v91, v20, v87
	v_fmac_f32_e32 v90, v21, v85
	v_fmac_f32_e32 v91, v21, v88
	v_fmac_f32_e32 v90, v22, v86
	v_fmac_f32_e32 v91, v22, v89
	v_cvt_pk_bf16_f32 v35, v90, v91
	global_store_dwordx4 v[14:15], v[32:35], off
	s_waitcnt vmcnt(7)
; __device__ __forceinline__ float bf2f(bfu h) { return __uint_as_float(((unsigned)h) << 16); }
; __device__ __forceinline__ unsigned pack2(float a, float b) { return (unsigned)f2bf(a) | ((unsigned)f2bf(b) << 16); }
; __device__ __forceinline__ float fexp(float x) { return __builtin_amdgcn_exp2f(x * 1.4426950408889634f); }
; __device__ __forceinline__ float frcp(float x) { return __builtin_amdgcn_rcpf(x); }
; __device__ void cd_fin_rows(const Params& p, int L, int row0, int nrows, const bool doC, const bool doD) {
;     ...
;     if (doD) {
;     const int head = lane >> 4;
;     float l0 = misc[MF_LSE + ((long)0 * MTOK + row) * 4 + head];
;     float l1 = misc[MF_LSE + ((long)1 * MTOK + row) * 4 + head];
;     float l2 = misc[MF_LSE + ((long)2 * MTOK + row) * 4 + head];
;     float mm = fmaxf(l0, fmaxf(l1, l2));
;     float e0 = fexp(l0 - mm), e1 = fexp(l1 - mm), e2 = fexp(l2 - mm);
;     float inv = frcp(e0 + e1 + e2);
;     e0 *= inv; e1 *= inv; e2 *= inv;
;     bf16x8 o0 = *(const bf16x8*)(pr + c0), o1 = *(const bf16x8*)(pr + 512 + c0), o2 = *(const bf16x8*)(pr + 1024 + c0);
;     float rd[8];
;     for (int e = 0; e < 8; ++e) rd[e] = e0 * bf2f((bfu)o0[e]) + e1 * bf2f((bfu)o1[e]) + e2 * bf2f((bfu)o2[e]);
;     uint4 wb; wb.x = pack2(rd[0], rd[1]); wb.y = pack2(rd[2], rd[3]); wb.z = pack2(rd[4], rd[5]); wb.w = pack2(rd[6], rd[7]);
;     *(uint4*)(pr + c0) = wb;
	v_max3_f32 v82, v23, v24, v25
	v_sub_f32_e32 v23, v23, v82
	v_sub_f32_e32 v24, v24, v82
	v_sub_f32_e32 v25, v25, v82
	v_mul_f32_e32 v23, 0x3fb8aa3b, v23
	v_mul_f32_e32 v24, 0x3fb8aa3b, v24
	v_mul_f32_e32 v25, 0x3fb8aa3b, v25
	v_exp_f32_e32 v23, v23
	v_exp_f32_e32 v24, v24
	v_exp_f32_e32 v25, v25
	v_add_f32_e32 v83, v23, v24
	v_add_f32_e32 v83, v25, v83
	v_rcp_f32_e32 v83, v83
	v_lshlrev_b32_e32 v84, 16, v44
	v_and_b32_e32 v87, 0xffff0000, v44
	v_lshlrev_b32_e32 v85, 16, v48
	v_and_b32_e32 v88, 0xffff0000, v48
	v_lshlrev_b32_e32 v86, 16, v52
	v_and_b32_e32 v89, 0xffff0000, v52
	v_mul_f32_e32 v23, v23, v83
	v_mul_f32_e32 v24, v24, v83
	v_mul_f32_e32 v25, v25, v83
	v_mul_f32_e32 v90, v23, v84
	v_mul_f32_e32 v91, v23, v87
	v_fmac_f32_e32 v90, v24, v85
	v_fmac_f32_e32 v91, v24, v88
	v_fmac_f32_e32 v90, v25, v86
	v_fmac_f32_e32 v91, v25, v89
	v_cvt_pk_bf16_f32 v44, v90, v91
	v_lshlrev_b32_e32 v84, 16, v45
	v_and_b32_e32 v87, 0xffff0000, v45
	v_lshlrev_b32_e32 v85, 16, v49
	v_and_b32_e32 v88, 0xffff0000, v49
	v_lshlrev_b32_e32 v86, 16, v53
	v_and_b32_e32 v89, 0xffff0000, v53
	v_mul_f32_e32 v90, v23, v84
	v_mul_f32_e32 v91, v23, v87
	v_fmac_f32_e32 v90, v24, v85
	v_fmac_f32_e32 v91, v24, v88
	v_fmac_f32_e32 v90, v25, v86
	v_fmac_f32_e32 v91, v25, v89
	v_cvt_pk_bf16_f32 v45, v90, v91
	v_lshlrev_b32_e32 v84, 16, v46
	v_and_b32_e32 v87, 0xffff0000, v46
	v_lshlrev_b32_e32 v85, 16, v50
	v_and_b32_e32 v88, 0xffff0000, v50
	v_lshlrev_b32_e32 v86, 16, v54
	v_and_b32_e32 v89, 0xffff0000, v54
	v_mul_f32_e32 v90, v23, v84
	v_mul_f32_e32 v91, v23, v87
	v_fmac_f32_e32 v90, v24, v85
	v_fmac_f32_e32 v91, v24, v88
	v_fmac_f32_e32 v90, v25, v86
	v_fmac_f32_e32 v91, v25, v89
	v_cvt_pk_bf16_f32 v46, v90, v91
	v_lshlrev_b32_e32 v84, 16, v47
	v_and_b32_e32 v87, 0xffff0000, v47
	v_lshlrev_b32_e32 v85, 16, v51
	v_and_b32_e32 v88, 0xffff0000, v51
	v_lshlrev_b32_e32 v86, 16, v55
	v_and_b32_e32 v89, 0xffff0000, v55
	v_mul_f32_e32 v90, v23, v84
	v_mul_f32_e32 v91, v23, v87
	v_fmac_f32_e32 v90, v24, v85
	v_fmac_f32_e32 v91, v24, v88
	v_fmac_f32_e32 v90, v25, v86
	v_fmac_f32_e32 v91, v25, v89
	v_cvt_pk_bf16_f32 v47, v90, v91
	global_store_dwordx4 v[16:17], v[44:47], off
	s_waitcnt vmcnt(5)
	v_max3_f32 v82, v26, v27, v28
	v_sub_f32_e32 v26, v26, v82
	v_sub_f32_e32 v27, v27, v82
	v_sub_f32_e32 v28, v28, v82
	v_mul_f32_e32 v26, 0x3fb8aa3b, v26
	v_mul_f32_e32 v27, 0x3fb8aa3b, v27
	v_mul_f32_e32 v28, 0x3fb8aa3b, v28
	v_exp_f32_e32 v26, v26
	v_exp_f32_e32 v27, v27
	v_exp_f32_e32 v28, v28
	v_add_f32_e32 v83, v26, v27
	v_add_f32_e32 v83, v28, v83
	v_rcp_f32_e32 v83, v83
	v_lshlrev_b32_e32 v84, 16, v56
	v_and_b32_e32 v87, 0xffff0000, v56
	v_lshlrev_b32_e32 v85, 16, v60
	v_and_b32_e32 v88, 0xffff0000, v60
	v_lshlrev_b32_e32 v86, 16, v64
	v_and_b32_e32 v89, 0xffff0000, v64
	v_mul_f32_e32 v26, v26, v83
	v_mul_f32_e32 v27, v27, v83
	v_mul_f32_e32 v28, v28, v83
	v_mul_f32_e32 v90, v26, v84
	v_mul_f32_e32 v91, v26, v87
	v_fmac_f32_e32 v90, v27, v85
	v_fmac_f32_e32 v91, v27, v88
	v_fmac_f32_e32 v90, v28, v86
	v_fmac_f32_e32 v91, v28, v89
	v_cvt_pk_bf16_f32 v56, v90, v91
	v_lshlrev_b32_e32 v84, 16, v57
	v_and_b32_e32 v87, 0xffff0000, v57
	v_lshlrev_b32_e32 v85, 16, v61
	v_and_b32_e32 v88, 0xffff0000, v61
	v_lshlrev_b32_e32 v86, 16, v65
	v_and_b32_e32 v89, 0xffff0000, v65
	v_mul_f32_e32 v90, v26, v84
	v_mul_f32_e32 v91, v26, v87
	v_fmac_f32_e32 v90, v27, v85
	v_fmac_f32_e32 v91, v27, v88
	v_fmac_f32_e32 v90, v28, v86
	v_fmac_f32_e32 v91, v28, v89
	v_cvt_pk_bf16_f32 v57, v90, v91
	v_lshlrev_b32_e32 v84, 16, v58
	v_and_b32_e32 v87, 0xffff0000, v58
	v_lshlrev_b32_e32 v85, 16, v62
	v_and_b32_e32 v88, 0xffff0000, v62
	v_lshlrev_b32_e32 v86, 16, v66
	v_and_b32_e32 v89, 0xffff0000, v66
	v_mul_f32_e32 v90, v26, v84
	v_mul_f32_e32 v91, v26, v87
	v_fmac_f32_e32 v90, v27, v85
	v_fmac_f32_e32 v91, v27, v88
	v_fmac_f32_e32 v90, v28, v86
	v_fmac_f32_e32 v91, v28, v89
	v_cvt_pk_bf16_f32 v58, v90, v91
	v_lshlrev_b32_e32 v84, 16, v59
	v_and_b32_e32 v87, 0xffff0000, v59
	v_lshlrev_b32_e32 v85, 16, v63
	v_and_b32_e32 v88, 0xffff0000, v63
	v_lshlrev_b32_e32 v86, 16, v67
	v_and_b32_e32 v89, 0xffff0000, v67
	v_mul_f32_e32 v90, v26, v84
	v_mul_f32_e32 v91, v26, v87
	v_fmac_f32_e32 v90, v27, v85
	v_fmac_f32_e32 v91, v27, v88
	v_fmac_f32_e32 v90, v28, v86
	v_fmac_f32_e32 v91, v28, v89
	v_cvt_pk_bf16_f32 v59, v90, v91
	global_store_dwordx4 v[18:19], v[56:59], off
	s_waitcnt vmcnt(3)
	v_max3_f32 v82, v29, v30, v31
	v_sub_f32_e32 v29, v29, v82
	v_sub_f32_e32 v30, v30, v82
	v_sub_f32_e32 v31, v31, v82
	v_mul_f32_e32 v29, 0x3fb8aa3b, v29
	v_mul_f32_e32 v30, 0x3fb8aa3b, v30
	v_mul_f32_e32 v31, 0x3fb8aa3b, v31
	v_exp_f32_e32 v29, v29
	v_exp_f32_e32 v30, v30
	v_exp_f32_e32 v31, v31
	v_add_f32_e32 v83, v29, v30
	v_add_f32_e32 v83, v31, v83
	v_rcp_f32_e32 v83, v83
	v_lshlrev_b32_e32 v84, 16, v68
	v_and_b32_e32 v87, 0xffff0000, v68
	v_lshlrev_b32_e32 v85, 16, v72
	v_and_b32_e32 v88, 0xffff0000, v72
	v_lshlrev_b32_e32 v86, 16, v76
	v_and_b32_e32 v89, 0xffff0000, v76
	v_mul_f32_e32 v29, v29, v83
	v_mul_f32_e32 v30, v30, v83
	v_mul_f32_e32 v31, v31, v83
	v_mul_f32_e32 v90, v29, v84
	v_mul_f32_e32 v91, v29, v87
	v_fmac_f32_e32 v90, v30, v85
	v_fmac_f32_e32 v91, v30, v88
	v_fmac_f32_e32 v90, v31, v86
	v_fmac_f32_e32 v91, v31, v89
	v_cvt_pk_bf16_f32 v68, v90, v91
	v_lshlrev_b32_e32 v84, 16, v69
	v_and_b32_e32 v87, 0xffff0000, v69
	v_lshlrev_b32_e32 v85, 16, v73
	v_and_b32_e32 v88, 0xffff0000, v73
	v_lshlrev_b32_e32 v86, 16, v77
	v_and_b32_e32 v89, 0xffff0000, v77
	v_mul_f32_e32 v90, v29, v84
	v_mul_f32_e32 v91, v29, v87
	v_fmac_f32_e32 v90, v30, v85
	v_fmac_f32_e32 v91, v30, v88
	v_fmac_f32_e32 v90, v31, v86
	v_fmac_f32_e32 v91, v31, v89
	v_cvt_pk_bf16_f32 v69, v90, v91
	v_lshlrev_b32_e32 v84, 16, v70
	v_and_b32_e32 v87, 0xffff0000, v70
	v_lshlrev_b32_e32 v85, 16, v74
	v_and_b32_e32 v88, 0xffff0000, v74
	v_lshlrev_b32_e32 v86, 16, v78
	v_and_b32_e32 v89, 0xffff0000, v78
	v_mul_f32_e32 v90, v29, v84
	v_mul_f32_e32 v91, v29, v87
	v_fmac_f32_e32 v90, v30, v85
	v_fmac_f32_e32 v91, v30, v88
	v_fmac_f32_e32 v90, v31, v86
	v_fmac_f32_e32 v91, v31, v89
	v_cvt_pk_bf16_f32 v70, v90, v91
	v_lshlrev_b32_e32 v84, 16, v71
	v_and_b32_e32 v87, 0xffff0000, v71
	v_lshlrev_b32_e32 v85, 16, v75
	v_and_b32_e32 v88, 0xffff0000, v75
	v_lshlrev_b32_e32 v86, 16, v79
	v_and_b32_e32 v89, 0xffff0000, v79
	v_mul_f32_e32 v90, v29, v84
	v_mul_f32_e32 v91, v29, v87
	v_fmac_f32_e32 v90, v30, v85
	v_fmac_f32_e32 v91, v30, v88
	v_fmac_f32_e32 v90, v31, v86
	v_fmac_f32_e32 v91, v31, v89
	v_cvt_pk_bf16_f32 v71, v90, v91
	global_store_dwordx4 v[80:81], v[68:71], off
	v_lshl_add_u64 v[8:9], v[8:9], 0, s[12:13]
	v_lshl_add_u64 v[10:11], v[10:11], 0, s[12:13]
	v_lshl_add_u64 v[12:13], v[12:13], 0, s[12:13]
	v_lshl_add_u64 v[14:15], v[14:15], 0, s[2:3]
	v_lshl_add_u64 v[16:17], v[16:17], 0, s[2:3]
	v_lshl_add_u64 v[18:19], v[18:19], 0, s[2:3]
	v_lshl_add_u64 v[80:81], v[80:81], 0, s[2:3]
	s_add_i32 s14, s14, -1
	s_cmp_lg_u32 s14, 0
	s_cbranch_scc1 .Lfd_loop

; __device__ __forceinline__ float bf2f(bfu h) { return __uint_as_float(((unsigned)h) << 16); }
; __device__ __forceinline__ unsigned pack2(float a, float b) { return (unsigned)f2bf(a) | ((unsigned)f2bf(b) << 16); }
; __device__ void ab_fin_rows(const Params& p, int L, int row0, int nrows, const bool doA, const bool doB) {
;     ...
;     if (doB) {
;     bf16x8 gb = *(const bf16x8*)(pr + 2048 + c0);
;     float rb[8];
;     for (int e = 0; e < 8; ++e) rb[e] = 0.f;
;     for (int j = 0; j < 3; ++j) {
;       int tt = t - 2 + j;
;       if (tt >= 0) {
;         const bfu* pj = pab + (row - 2 + j) * 3584;
;         bf16x8 gc = *(const bf16x8*)(pj + 2560 + c0);
;         bf16x8 si = *(const bf16x8*)(pj + 3072 + c0);
;         for (int e = 0; e < 8; ++e) rb[e] += p.sc_conv_w[(long)li * 3 * 512 + j * 512 + c0 + e] * (bf2f((bfu)gc[e]) * bf2f((bfu)si[e]));
;       }
;     }
;     for (int e = 0; e < 8; ++e) rb[e] *= bf2f((bfu)gb[e]);
;     uint4 wb; wb.x = pack2(rb[0], rb[1]); wb.y = pack2(rb[2], rb[3]); wb.z = pack2(rb[4], rb[5]); wb.w = pack2(rb[6], rb[7]);
;     *(uint4*)(pr + 1024 + c0) = wb;
;     }
.LBB0_356:
	s_andn2_b64 vcc, exec, s[0:1]
	s_cbranch_vccnz .LBB0_350
	v_mbcnt_lo_u32_b32 v0, -1, 0
	v_mbcnt_hi_u32_b32 v0, -1, v0
	s_movk_i32 s0, 0x80
	s_waitcnt lgkmcnt(0)
	v_or_b32_e32 v2, s33, v0
	s_nop 0
	v_ashrrev_i32_e32 v32, 6, v2
	v_cmp_gt_i32_e32 vcc, s0, v32
	s_and_saveexec_b64 s[0:1], vcc
	s_cbranch_execz .LBB0_349
	v_readlane_b32 s36, v254, 17
	v_readlane_b32 s38, v254, 19
	v_readlane_b32 s39, v254, 20
	v_readlane_b32 s37, v254, 18
	v_readlane_b32 s40, v254, 21
	v_readlane_b32 s41, v254, 22
	v_readlane_b32 s42, v254, 23
	v_readlane_b32 s43, v254, 24
	v_readlane_b32 s44, v254, 25
	v_readlane_b32 s45, v254, 26
	v_readlane_b32 s46, v254, 27
	v_readlane_b32 s47, v254, 28
	v_readlane_b32 s48, v254, 29
	v_readlane_b32 s49, v254, 30
	v_readlane_b32 s50, v254, 31
	v_readlane_b32 s51, v254, 32
	v_and_b32_e32 v0, 63, v2
	v_readlane_b32 s2, v254, 57
	s_mulk_i32 s2, 0x600
	v_lshl_add_u32 v3, v0, 3, s2
	v_lshlrev_b32_e32 v4, 2, v3
	v_mov_b32_e32 v5, 0
	v_lshl_add_u64 v[4:5], s[38:39], 0, v[4:5]
	s_mov_b64 s[12:13], 0x1000
	v_lshl_add_u64 v[6:7], v[4:5], 0, s[12:13]
	global_load_dwordx4 v[40:43], v[4:5], off
	global_load_dwordx4 v[44:47], v[4:5], off offset:16
	global_load_dwordx4 v[48:51], v[4:5], off offset:2048
	global_load_dwordx4 v[52:55], v[4:5], off offset:2064
	global_load_dwordx4 v[56:59], v[6:7], off
	global_load_dwordx4 v[60:63], v[6:7], off offset:16
	s_lshr_b32 s3, s33, 6
	s_add_i32 s3, s3, s18
	v_mov_b32_e32 v8, s3
	s_movk_i32 s2, 0x1c00
	v_mad_u64_u32 v[8:9], vcc, v8, s2, 0
	v_lshlrev_b32_e32 v10, 4, v0
	v_mov_b32_e32 v11, 0
	v_lshl_add_u64 v[8:9], v[8:9], 0, v[10:11]
	v_readlane_b32 s12, v253, 46
	v_readlane_b32 s13, v253, 47
	s_nop 1
	v_lshl_add_u64 v[8:9], s[12:13], 0, v[8:9]
	s_mov_b64 s[12:13], 0xe000
	s_mov_b64 s[14:15], 0x1c00
	v_mov_b64_e32 v[64:65], v[8:9]
	v_lshl_add_u64 v[70:71], v[64:65], 0, s[12:13]
	v_lshl_add_u64 v[76:77], v[70:71], 0, s[12:13]
	v_lshl_add_u64 v[82:83], v[76:77], 0, s[12:13]
	v_lshl_add_u64 v[66:67], v[64:65], 0, s[14:15]
	v_lshl_add_u64 v[72:73], v[70:71], 0, s[14:15]
	v_lshl_add_u64 v[78:79], v[76:77], 0, s[14:15]
	v_lshl_add_u64 v[84:85], v[82:83], 0, s[14:15]
	s_mov_b64 s[14:15], 0x1800
	v_lshl_add_u64 v[68:69], v[66:67], 0, s[14:15]
	v_lshl_add_u64 v[74:75], v[72:73], 0, s[14:15]
	v_lshl_add_u64 v[80:81], v[78:79], 0, s[14:15]
	v_lshl_add_u64 v[86:87], v[84:85], 0, s[14:15]
	v_mov_b32_e32 v10, 0x38000
	v_mov_b32_e32 v11, 0
	s_movk_i32 s2, 4
.Lfb_loop:
	global_load_dwordx4 v[88:91], v[64:65], off
	global_load_dwordx4 v[92:95], v[64:65], off offset:1024
	global_load_dwordx4 v[96:99], v[66:67], off
	global_load_dwordx4 v[100:103], v[66:67], off offset:1024
	global_load_dwordx4 v[104:107], v[68:69], off offset:1024
	global_load_dwordx4 v[108:111], v[68:69], off offset:2048
	global_load_dwordx4 v[112:115], v[68:69], off
	global_load_dwordx4 v[116:119], v[70:71], off
	global_load_dwordx4 v[120:123], v[70:71], off offset:1024
	global_load_dwordx4 v[124:127], v[72:73], off
	global_load_dwordx4 v[128:131], v[72:73], off offset:1024
	global_load_dwordx4 v[132:135], v[74:75], off offset:1024
	global_load_dwordx4 v[136:139], v[74:75], off offset:2048
	global_load_dwordx4 v[140:143], v[74:75], off
	global_load_dwordx4 v[144:147], v[76:77], off
	global_load_dwordx4 v[148:151], v[76:77], off offset:1024
	global_load_dwordx4 v[152:155], v[78:79], off
	global_load_dwordx4 v[156:159], v[78:79], off offset:1024
	global_load_dwordx4 v[160:163], v[80:81], off offset:1024
	global_load_dwordx4 v[164:167], v[80:81], off offset:2048
	global_load_dwordx4 v[168:171], v[80:81], off
	global_load_dwordx4 v[172:175], v[82:83], off
	global_load_dwordx4 v[176:179], v[82:83], off offset:1024
	global_load_dwordx4 v[180:183], v[84:85], off
	global_load_dwordx4 v[184:187], v[84:85], off offset:1024
	global_load_dwordx4 v[188:191], v[86:87], off offset:1024
	global_load_dwordx4 v[192:195], v[86:87], off offset:2048
	global_load_dwordx4 v[196:199], v[86:87], off
	s_and_b32 s12, s3, 0xfff
	s_cmp_gt_u32 s12, 1
	s_cselect_b64 s[14:15], -1, 0
	s_cmp_gt_u32 s12, 0
	s_cselect_b64 s[12:13], -1, 0
	s_waitcnt vmcnt(21)
	v_cndmask_b32_e64 v88, 0, v88, s[14:15]
	v_cndmask_b32_e64 v89, 0, v89, s[14:15]
	v_cndmask_b32_e64 v90, 0, v90, s[14:15]
	v_cndmask_b32_e64 v91, 0, v91, s[14:15]
	v_cndmask_b32_e64 v96, 0, v96, s[12:13]
	v_cndmask_b32_e64 v97, 0, v97, s[12:13]
	v_cndmask_b32_e64 v98, 0, v98, s[12:13]
	v_cndmask_b32_e64 v99, 0, v99, s[12:13]
	v_lshlrev_b32_e32 v12, 16, v88
	v_and_b32_e32 v13, 0xffff0000, v88
	v_lshlrev_b32_e32 v14, 16, v92
	v_and_b32_e32 v15, 0xffff0000, v92
	v_lshlrev_b32_e32 v16, 16, v96
	v_and_b32_e32 v17, 0xffff0000, v96
	v_lshlrev_b32_e32 v18, 16, v100
	v_and_b32_e32 v19, 0xffff0000, v100
	v_lshlrev_b32_e32 v20, 16, v104
	v_and_b32_e32 v21, 0xffff0000, v104
	v_lshlrev_b32_e32 v22, 16, v108
	v_and_b32_e32 v23, 0xffff0000, v108
	v_lshlrev_b32_e32 v24, 16, v112
	v_and_b32_e32 v25, 0xffff0000, v112
	v_pk_mul_f32 v[12:13], v[12:13], v[14:15]
	v_pk_mul_f32 v[16:17], v[16:17], v[18:19]
	v_pk_mul_f32 v[20:21], v[20:21], v[22:23]
	v_pk_mul_f32 v[12:13], v[40:41], v[12:13]
	v_pk_fma_f32 v[12:13], v[48:49], v[16:17], v[12:13]
	v_pk_fma_f32 v[12:13], v[56:57], v[20:21], v[12:13]
	v_pk_mul_f32 v[12:13], v[12:13], v[24:25]
	v_cvt_pk_bf16_f32 v88, v12, v13
	v_lshlrev_b32_e32 v12, 16, v89
	v_and_b32_e32 v13, 0xffff0000, v89
	v_lshlrev_b32_e32 v14, 16, v93
	v_and_b32_e32 v15, 0xffff0000, v93
	v_lshlrev_b32_e32 v16, 16, v97
	v_and_b32_e32 v17, 0xffff0000, v97
	v_lshlrev_b32_e32 v18, 16, v101
	v_and_b32_e32 v19, 0xffff0000, v101
	v_lshlrev_b32_e32 v20, 16, v105
	v_and_b32_e32 v21, 0xffff0000, v105
	v_lshlrev_b32_e32 v22, 16, v109
; __device__ __forceinline__ float bf2f(bfu h) { return __uint_as_float(((unsigned)h) << 16); }
; __device__ __forceinline__ unsigned pack2(float a, float b) { return (unsigned)f2bf(a) | ((unsigned)f2bf(b) << 16); }
; __device__ void ab_fin_rows(const Params& p, int L, int row0, int nrows, const bool doA, const bool doB) {
;     ...
;     if (doB) {
;     bf16x8 gb = *(const bf16x8*)(pr + 2048 + c0);
;     float rb[8];
;     for (int e = 0; e < 8; ++e) rb[e] = 0.f;
;     for (int j = 0; j < 3; ++j) {
;       int tt = t - 2 + j;
;       if (tt >= 0) {
;         const bfu* pj = pab + (row - 2 + j) * 3584;
;         bf16x8 gc = *(const bf16x8*)(pj + 2560 + c0);
;         bf16x8 si = *(const bf16x8*)(pj + 3072 + c0);
;         for (int e = 0; e < 8; ++e) rb[e] += p.sc_conv_w[(long)li * 3 * 512 + j * 512 + c0 + e] * (bf2f((bfu)gc[e]) * bf2f((bfu)si[e]));
;       }
;     }
;     for (int e = 0; e < 8; ++e) rb[e] *= bf2f((bfu)gb[e]);
;     uint4 wb; wb.x = pack2(rb[0], rb[1]); wb.y = pack2(rb[2], rb[3]); wb.z = pack2(rb[4], rb[5]); wb.w = pack2(rb[6], rb[7]);
;     *(uint4*)(pr + 1024 + c0) = wb;
;     }
	v_and_b32_e32 v23, 0xffff0000, v109
	v_lshlrev_b32_e32 v24, 16, v113
	v_and_b32_e32 v25, 0xffff0000, v113
	v_pk_mul_f32 v[12:13], v[12:13], v[14:15]
	v_pk_mul_f32 v[16:17], v[16:17], v[18:19]
	v_pk_mul_f32 v[20:21], v[20:21], v[22:23]
	v_pk_mul_f32 v[12:13], v[42:43], v[12:13]
	v_pk_fma_f32 v[12:13], v[50:51], v[16:17], v[12:13]
	v_pk_fma_f32 v[12:13], v[58:59], v[20:21], v[12:13]
	v_pk_mul_f32 v[12:13], v[12:13], v[24:25]
	v_cvt_pk_bf16_f32 v89, v12, v13
	v_lshlrev_b32_e32 v12, 16, v90
	v_and_b32_e32 v13, 0xffff0000, v90
	v_lshlrev_b32_e32 v14, 16, v94
	v_and_b32_e32 v15, 0xffff0000, v94
	v_lshlrev_b32_e32 v16, 16, v98
	v_and_b32_e32 v17, 0xffff0000, v98
	v_lshlrev_b32_e32 v18, 16, v102
	v_and_b32_e32 v19, 0xffff0000, v102
	v_lshlrev_b32_e32 v20, 16, v106
	v_and_b32_e32 v21, 0xffff0000, v106
	v_lshlrev_b32_e32 v22, 16, v110
	v_and_b32_e32 v23, 0xffff0000, v110
	v_lshlrev_b32_e32 v24, 16, v114
	v_and_b32_e32 v25, 0xffff0000, v114
	v_pk_mul_f32 v[12:13], v[12:13], v[14:15]
	v_pk_mul_f32 v[16:17], v[16:17], v[18:19]
	v_pk_mul_f32 v[20:21], v[20:21], v[22:23]
	v_pk_mul_f32 v[12:13], v[44:45], v[12:13]
	v_pk_fma_f32 v[12:13], v[52:53], v[16:17], v[12:13]
	v_pk_fma_f32 v[12:13], v[60:61], v[20:21], v[12:13]
	v_pk_mul_f32 v[12:13], v[12:13], v[24:25]
	v_cvt_pk_bf16_f32 v90, v12, v13
	v_lshlrev_b32_e32 v12, 16, v91
	v_and_b32_e32 v13, 0xffff0000, v91
	v_lshlrev_b32_e32 v14, 16, v95
	v_and_b32_e32 v15, 0xffff0000, v95
	v_lshlrev_b32_e32 v16, 16, v99
	v_and_b32_e32 v17, 0xffff0000, v99
	v_lshlrev_b32_e32 v18, 16, v103
	v_and_b32_e32 v19, 0xffff0000, v103
	v_lshlrev_b32_e32 v20, 16, v107
	v_and_b32_e32 v21, 0xffff0000, v107
	v_lshlrev_b32_e32 v22, 16, v111
	v_and_b32_e32 v23, 0xffff0000, v111
	v_lshlrev_b32_e32 v24, 16, v115
	v_and_b32_e32 v25, 0xffff0000, v115
	v_pk_mul_f32 v[12:13], v[12:13], v[14:15]
	v_pk_mul_f32 v[16:17], v[16:17], v[18:19]
	v_pk_mul_f32 v[20:21], v[20:21], v[22:23]
	v_pk_mul_f32 v[12:13], v[46:47], v[12:13]
	v_pk_fma_f32 v[12:13], v[54:55], v[16:17], v[12:13]
	v_pk_fma_f32 v[12:13], v[62:63], v[20:21], v[12:13]
	v_pk_mul_f32 v[12:13], v[12:13], v[24:25]
	v_cvt_pk_bf16_f32 v91, v12, v13
	global_store_dwordx4 v[68:69], v[88:91], off offset:-2048
	s_waitcnt vmcnt(15)
	v_lshlrev_b32_e32 v12, 16, v116
	v_and_b32_e32 v13, 0xffff0000, v116
	v_lshlrev_b32_e32 v14, 16, v120
	v_and_b32_e32 v15, 0xffff0000, v120
	v_lshlrev_b32_e32 v16, 16, v124
	v_and_b32_e32 v17, 0xffff0000, v124
	v_lshlrev_b32_e32 v18, 16, v128
	v_and_b32_e32 v19, 0xffff0000, v128
	v_lshlrev_b32_e32 v20, 16, v132
	v_and_b32_e32 v21, 0xffff0000, v132
	v_lshlrev_b32_e32 v22, 16, v136
	v_and_b32_e32 v23, 0xffff0000, v136
	v_lshlrev_b32_e32 v24, 16, v140
	v_and_b32_e32 v25, 0xffff0000, v140
	v_pk_mul_f32 v[12:13], v[12:13], v[14:15]
	v_pk_mul_f32 v[16:17], v[16:17], v[18:19]
	v_pk_mul_f32 v[20:21], v[20:21], v[22:23]
	v_pk_mul_f32 v[12:13], v[40:41], v[12:13]
	v_pk_fma_f32 v[12:13], v[48:49], v[16:17], v[12:13]
	v_pk_fma_f32 v[12:13], v[56:57], v[20:21], v[12:13]
	v_pk_mul_f32 v[12:13], v[12:13], v[24:25]
	v_cvt_pk_bf16_f32 v116, v12, v13
	v_lshlrev_b32_e32 v12, 16, v117
	v_and_b32_e32 v13, 0xffff0000, v117
	v_lshlrev_b32_e32 v14, 16, v121
	v_and_b32_e32 v15, 0xffff0000, v121
	v_lshlrev_b32_e32 v16, 16, v125
	v_and_b32_e32 v17, 0xffff0000, v125
	v_lshlrev_b32_e32 v18, 16, v129
	v_and_b32_e32 v19, 0xffff0000, v129
	v_lshlrev_b32_e32 v20, 16, v133
	v_and_b32_e32 v21, 0xffff0000, v133
	v_lshlrev_b32_e32 v22, 16, v137
	v_and_b32_e32 v23, 0xffff0000, v137
	v_lshlrev_b32_e32 v24, 16, v141
	v_and_b32_e32 v25, 0xffff0000, v141
	v_pk_mul_f32 v[12:13], v[12:13], v[14:15]
	v_pk_mul_f32 v[16:17], v[16:17], v[18:19]
	v_pk_mul_f32 v[20:21], v[20:21], v[22:23]
	v_pk_mul_f32 v[12:13], v[42:43], v[12:13]
	v_pk_fma_f32 v[12:13], v[50:51], v[16:17], v[12:13]
	v_pk_fma_f32 v[12:13], v[58:59], v[20:21], v[12:13]
	v_pk_mul_f32 v[12:13], v[12:13], v[24:25]
	v_cvt_pk_bf16_f32 v117, v12, v13
	v_lshlrev_b32_e32 v12, 16, v118
	v_and_b32_e32 v13, 0xffff0000, v118
	v_lshlrev_b32_e32 v14, 16, v122
	v_and_b32_e32 v15, 0xffff0000, v122
	v_lshlrev_b32_e32 v16, 16, v126
	v_and_b32_e32 v17, 0xffff0000, v126
	v_lshlrev_b32_e32 v18, 16, v130
	v_and_b32_e32 v19, 0xffff0000, v130
	v_lshlrev_b32_e32 v20, 16, v134
	v_and_b32_e32 v21, 0xffff0000, v134
	v_lshlrev_b32_e32 v22, 16, v138
	v_and_b32_e32 v23, 0xffff0000, v138
	v_lshlrev_b32_e32 v24, 16, v142
	v_and_b32_e32 v25, 0xffff0000, v142
	v_pk_mul_f32 v[12:13], v[12:13], v[14:15]
	v_pk_mul_f32 v[16:17], v[16:17], v[18:19]
	v_pk_mul_f32 v[20:21], v[20:21], v[22:23]
	v_pk_mul_f32 v[12:13], v[44:45], v[12:13]
	v_pk_fma_f32 v[12:13], v[52:53], v[16:17], v[12:13]
	v_pk_fma_f32 v[12:13], v[60:61], v[20:21], v[12:13]
	v_pk_mul_f32 v[12:13], v[12:13], v[24:25]
	v_cvt_pk_bf16_f32 v118, v12, v13
	v_lshlrev_b32_e32 v12, 16, v119
	v_and_b32_e32 v13, 0xffff0000, v119
	v_lshlrev_b32_e32 v14, 16, v123
	v_and_b32_e32 v15, 0xffff0000, v123
	v_lshlrev_b32_e32 v16, 16, v127
	v_and_b32_e32 v17, 0xffff0000, v127
	v_lshlrev_b32_e32 v18, 16, v131
	v_and_b32_e32 v19, 0xffff0000, v131
	v_lshlrev_b32_e32 v20, 16, v135
	v_and_b32_e32 v21, 0xffff0000, v135
	v_lshlrev_b32_e32 v22, 16, v139
	v_and_b32_e32 v23, 0xffff0000, v139
	v_lshlrev_b32_e32 v24, 16, v143
	v_and_b32_e32 v25, 0xffff0000, v143
	v_pk_mul_f32 v[12:13], v[12:13], v[14:15]
	v_pk_mul_f32 v[16:17], v[16:17], v[18:19]
	v_pk_mul_f32 v[20:21], v[20:21], v[22:23]
	v_pk_mul_f32 v[12:13], v[46:47], v[12:13]
	v_pk_fma_f32 v[12:13], v[54:55], v[16:17], v[12:13]
	v_pk_fma_f32 v[12:13], v[62:63], v[20:21], v[12:13]
	v_pk_mul_f32 v[12:13], v[12:13], v[24:25]
	v_cvt_pk_bf16_f32 v119, v12, v13
	global_store_dwordx4 v[74:75], v[116:119], off offset:-2048
	s_waitcnt vmcnt(9)
; __device__ __forceinline__ float bf2f(bfu h) { return __uint_as_float(((unsigned)h) << 16); }
; __device__ __forceinline__ unsigned pack2(float a, float b) { return (unsigned)f2bf(a) | ((unsigned)f2bf(b) << 16); }
; __device__ void ab_fin_rows(const Params& p, int L, int row0, int nrows, const bool doA, const bool doB) {
;     ...
;     if (doB) {
;     bf16x8 gb = *(const bf16x8*)(pr + 2048 + c0);
;     float rb[8];
;     for (int e = 0; e < 8; ++e) rb[e] = 0.f;
;     for (int j = 0; j < 3; ++j) {
;       int tt = t - 2 + j;
;       if (tt >= 0) {
;         const bfu* pj = pab + (row - 2 + j) * 3584;
;         bf16x8 gc = *(const bf16x8*)(pj + 2560 + c0);
;         bf16x8 si = *(const bf16x8*)(pj + 3072 + c0);
;         for (int e = 0; e < 8; ++e) rb[e] += p.sc_conv_w[(long)li * 3 * 512 + j * 512 + c0 + e] * (bf2f((bfu)gc[e]) * bf2f((bfu)si[e]));
;       }
;     }
;     for (int e = 0; e < 8; ++e) rb[e] *= bf2f((bfu)gb[e]);
;     uint4 wb; wb.x = pack2(rb[0], rb[1]); wb.y = pack2(rb[2], rb[3]); wb.z = pack2(rb[4], rb[5]); wb.w = pack2(rb[6], rb[7]);
;     *(uint4*)(pr + 1024 + c0) = wb;
;     }
	v_lshlrev_b32_e32 v12, 16, v144
	v_and_b32_e32 v13, 0xffff0000, v144
	v_lshlrev_b32_e32 v14, 16, v148
	v_and_b32_e32 v15, 0xffff0000, v148
	v_lshlrev_b32_e32 v16, 16, v152
	v_and_b32_e32 v17, 0xffff0000, v152
	v_lshlrev_b32_e32 v18, 16, v156
	v_and_b32_e32 v19, 0xffff0000, v156
	v_lshlrev_b32_e32 v20, 16, v160
	v_and_b32_e32 v21, 0xffff0000, v160
	v_lshlrev_b32_e32 v22, 16, v164
	v_and_b32_e32 v23, 0xffff0000, v164
	v_lshlrev_b32_e32 v24, 16, v168
	v_and_b32_e32 v25, 0xffff0000, v168
	v_pk_mul_f32 v[12:13], v[12:13], v[14:15]
	v_pk_mul_f32 v[16:17], v[16:17], v[18:19]
	v_pk_mul_f32 v[20:21], v[20:21], v[22:23]
	v_pk_mul_f32 v[12:13], v[40:41], v[12:13]
	v_pk_fma_f32 v[12:13], v[48:49], v[16:17], v[12:13]
	v_pk_fma_f32 v[12:13], v[56:57], v[20:21], v[12:13]
	v_pk_mul_f32 v[12:13], v[12:13], v[24:25]
	v_cvt_pk_bf16_f32 v144, v12, v13
	v_lshlrev_b32_e32 v12, 16, v145
	v_and_b32_e32 v13, 0xffff0000, v145
	v_lshlrev_b32_e32 v14, 16, v149
	v_and_b32_e32 v15, 0xffff0000, v149
	v_lshlrev_b32_e32 v16, 16, v153
	v_and_b32_e32 v17, 0xffff0000, v153
	v_lshlrev_b32_e32 v18, 16, v157
	v_and_b32_e32 v19, 0xffff0000, v157
	v_lshlrev_b32_e32 v20, 16, v161
	v_and_b32_e32 v21, 0xffff0000, v161
	v_lshlrev_b32_e32 v22, 16, v165
	v_and_b32_e32 v23, 0xffff0000, v165
	v_lshlrev_b32_e32 v24, 16, v169
	v_and_b32_e32 v25, 0xffff0000, v169
	v_pk_mul_f32 v[12:13], v[12:13], v[14:15]
	v_pk_mul_f32 v[16:17], v[16:17], v[18:19]
	v_pk_mul_f32 v[20:21], v[20:21], v[22:23]
	v_pk_mul_f32 v[12:13], v[42:43], v[12:13]
	v_pk_fma_f32 v[12:13], v[50:51], v[16:17], v[12:13]
	v_pk_fma_f32 v[12:13], v[58:59], v[20:21], v[12:13]
	v_pk_mul_f32 v[12:13], v[12:13], v[24:25]
	v_cvt_pk_bf16_f32 v145, v12, v13
	v_lshlrev_b32_e32 v12, 16, v146
	v_and_b32_e32 v13, 0xffff0000, v146
	v_lshlrev_b32_e32 v14, 16, v150
	v_and_b32_e32 v15, 0xffff0000, v150
	v_lshlrev_b32_e32 v16, 16, v154
	v_and_b32_e32 v17, 0xffff0000, v154
	v_lshlrev_b32_e32 v18, 16, v158
	v_and_b32_e32 v19, 0xffff0000, v158
	v_lshlrev_b32_e32 v20, 16, v162
	v_and_b32_e32 v21, 0xffff0000, v162
	v_lshlrev_b32_e32 v22, 16, v166
	v_and_b32_e32 v23, 0xffff0000, v166
	v_lshlrev_b32_e32 v24, 16, v170
	v_and_b32_e32 v25, 0xffff0000, v170
	v_pk_mul_f32 v[12:13], v[12:13], v[14:15]
	v_pk_mul_f32 v[16:17], v[16:17], v[18:19]
	v_pk_mul_f32 v[20:21], v[20:21], v[22:23]
	v_pk_mul_f32 v[12:13], v[44:45], v[12:13]
	v_pk_fma_f32 v[12:13], v[52:53], v[16:17], v[12:13]
	v_pk_fma_f32 v[12:13], v[60:61], v[20:21], v[12:13]
	v_pk_mul_f32 v[12:13], v[12:13], v[24:25]
	v_cvt_pk_bf16_f32 v146, v12, v13
	v_lshlrev_b32_e32 v12, 16, v147
	v_and_b32_e32 v13, 0xffff0000, v147
	v_lshlrev_b32_e32 v14, 16, v151
	v_and_b32_e32 v15, 0xffff0000, v151
	v_lshlrev_b32_e32 v16, 16, v155
	v_and_b32_e32 v17, 0xffff0000, v155
	v_lshlrev_b32_e32 v18, 16, v159
	v_and_b32_e32 v19, 0xffff0000, v159
	v_lshlrev_b32_e32 v20, 16, v163
	v_and_b32_e32 v21, 0xffff0000, v163
	v_lshlrev_b32_e32 v22, 16, v167
	v_and_b32_e32 v23, 0xffff0000, v167
	v_lshlrev_b32_e32 v24, 16, v171
	v_and_b32_e32 v25, 0xffff0000, v171
	v_pk_mul_f32 v[12:13], v[12:13], v[14:15]
	v_pk_mul_f32 v[16:17], v[16:17], v[18:19]
	v_pk_mul_f32 v[20:21], v[20:21], v[22:23]
	v_pk_mul_f32 v[12:13], v[46:47], v[12:13]
	v_pk_fma_f32 v[12:13], v[54:55], v[16:17], v[12:13]
	v_pk_fma_f32 v[12:13], v[62:63], v[20:21], v[12:13]
	v_pk_mul_f32 v[12:13], v[12:13], v[24:25]
	v_cvt_pk_bf16_f32 v147, v12, v13
	global_store_dwordx4 v[80:81], v[144:147], off offset:-2048
	s_waitcnt vmcnt(3)
; __device__ __forceinline__ float bf2f(bfu h) { return __uint_as_float(((unsigned)h) << 16); }
; __device__ __forceinline__ unsigned pack2(float a, float b) { return (unsigned)f2bf(a) | ((unsigned)f2bf(b) << 16); }
; __device__ void ab_fin_rows(const Params& p, int L, int row0, int nrows, const bool doA, const bool doB) {
;     ...
;     if (doB) {
;     bf16x8 gb = *(const bf16x8*)(pr + 2048 + c0);
;     float rb[8];
;     for (int e = 0; e < 8; ++e) rb[e] = 0.f;
;     for (int j = 0; j < 3; ++j) {
;       int tt = t - 2 + j;
;       if (tt >= 0) {
;         const bfu* pj = pab + (row - 2 + j) * 3584;
;         bf16x8 gc = *(const bf16x8*)(pj + 2560 + c0);
;         bf16x8 si = *(const bf16x8*)(pj + 3072 + c0);
;         for (int e = 0; e < 8; ++e) rb[e] += p.sc_conv_w[(long)li * 3 * 512 + j * 512 + c0 + e] * (bf2f((bfu)gc[e]) * bf2f((bfu)si[e]));
;       }
;     }
;     for (int e = 0; e < 8; ++e) rb[e] *= bf2f((bfu)gb[e]);
;     uint4 wb; wb.x = pack2(rb[0], rb[1]); wb.y = pack2(rb[2], rb[3]); wb.z = pack2(rb[4], rb[5]); wb.w = pack2(rb[6], rb[7]);
;     *(uint4*)(pr + 1024 + c0) = wb;
;     }
	v_lshlrev_b32_e32 v12, 16, v172
	v_and_b32_e32 v13, 0xffff0000, v172
	v_lshlrev_b32_e32 v14, 16, v176
	v_and_b32_e32 v15, 0xffff0000, v176
	v_lshlrev_b32_e32 v16, 16, v180
	v_and_b32_e32 v17, 0xffff0000, v180
	v_lshlrev_b32_e32 v18, 16, v184
	v_and_b32_e32 v19, 0xffff0000, v184
	v_lshlrev_b32_e32 v20, 16, v188
	v_and_b32_e32 v21, 0xffff0000, v188
	v_lshlrev_b32_e32 v22, 16, v192
	v_and_b32_e32 v23, 0xffff0000, v192
	v_lshlrev_b32_e32 v24, 16, v196
	v_and_b32_e32 v25, 0xffff0000, v196
	v_pk_mul_f32 v[12:13], v[12:13], v[14:15]
	v_pk_mul_f32 v[16:17], v[16:17], v[18:19]
	v_pk_mul_f32 v[20:21], v[20:21], v[22:23]
	v_pk_mul_f32 v[12:13], v[40:41], v[12:13]
	v_pk_fma_f32 v[12:13], v[48:49], v[16:17], v[12:13]
	v_pk_fma_f32 v[12:13], v[56:57], v[20:21], v[12:13]
	v_pk_mul_f32 v[12:13], v[12:13], v[24:25]
	v_cvt_pk_bf16_f32 v172, v12, v13
	v_lshlrev_b32_e32 v12, 16, v173
	v_and_b32_e32 v13, 0xffff0000, v173
	v_lshlrev_b32_e32 v14, 16, v177
	v_and_b32_e32 v15, 0xffff0000, v177
	v_lshlrev_b32_e32 v16, 16, v181
	v_and_b32_e32 v17, 0xffff0000, v181
	v_lshlrev_b32_e32 v18, 16, v185
	v_and_b32_e32 v19, 0xffff0000, v185
	v_lshlrev_b32_e32 v20, 16, v189
	v_and_b32_e32 v21, 0xffff0000, v189
	v_lshlrev_b32_e32 v22, 16, v193
	v_and_b32_e32 v23, 0xffff0000, v193
	v_lshlrev_b32_e32 v24, 16, v197
	v_and_b32_e32 v25, 0xffff0000, v197
	v_pk_mul_f32 v[12:13], v[12:13], v[14:15]
	v_pk_mul_f32 v[16:17], v[16:17], v[18:19]
	v_pk_mul_f32 v[20:21], v[20:21], v[22:23]
	v_pk_mul_f32 v[12:13], v[42:43], v[12:13]
	v_pk_fma_f32 v[12:13], v[50:51], v[16:17], v[12:13]
	v_pk_fma_f32 v[12:13], v[58:59], v[20:21], v[12:13]
	v_pk_mul_f32 v[12:13], v[12:13], v[24:25]
	v_cvt_pk_bf16_f32 v173, v12, v13
	v_lshlrev_b32_e32 v12, 16, v174
	v_and_b32_e32 v13, 0xffff0000, v174
	v_lshlrev_b32_e32 v14, 16, v178
	v_and_b32_e32 v15, 0xffff0000, v178
	v_lshlrev_b32_e32 v16, 16, v182
	v_and_b32_e32 v17, 0xffff0000, v182
	v_lshlrev_b32_e32 v18, 16, v186
	v_and_b32_e32 v19, 0xffff0000, v186
	v_lshlrev_b32_e32 v20, 16, v190
	v_and_b32_e32 v21, 0xffff0000, v190
	v_lshlrev_b32_e32 v22, 16, v194
	v_and_b32_e32 v23, 0xffff0000, v194
	v_lshlrev_b32_e32 v24, 16, v198
	v_and_b32_e32 v25, 0xffff0000, v198
	v_pk_mul_f32 v[12:13], v[12:13], v[14:15]
	v_pk_mul_f32 v[16:17], v[16:17], v[18:19]
	v_pk_mul_f32 v[20:21], v[20:21], v[22:23]
	v_pk_mul_f32 v[12:13], v[44:45], v[12:13]
	v_pk_fma_f32 v[12:13], v[52:53], v[16:17], v[12:13]
	v_pk_fma_f32 v[12:13], v[60:61], v[20:21], v[12:13]
	v_pk_mul_f32 v[12:13], v[12:13], v[24:25]
	v_cvt_pk_bf16_f32 v174, v12, v13
	v_lshlrev_b32_e32 v12, 16, v175
	v_and_b32_e32 v13, 0xffff0000, v175
	v_lshlrev_b32_e32 v14, 16, v179
	v_and_b32_e32 v15, 0xffff0000, v179
	v_lshlrev_b32_e32 v16, 16, v183
	v_and_b32_e32 v17, 0xffff0000, v183
	v_lshlrev_b32_e32 v18, 16, v187
	v_and_b32_e32 v19, 0xffff0000, v187
	v_lshlrev_b32_e32 v20, 16, v191
	v_and_b32_e32 v21, 0xffff0000, v191
	v_lshlrev_b32_e32 v22, 16, v195
	v_and_b32_e32 v23, 0xffff0000, v195
	v_lshlrev_b32_e32 v24, 16, v199
	v_and_b32_e32 v25, 0xffff0000, v199
	v_pk_mul_f32 v[12:13], v[12:13], v[14:15]
	v_pk_mul_f32 v[16:17], v[16:17], v[18:19]
	v_pk_mul_f32 v[20:21], v[20:21], v[22:23]
	v_pk_mul_f32 v[12:13], v[46:47], v[12:13]
	v_pk_fma_f32 v[12:13], v[54:55], v[16:17], v[12:13]
	v_pk_fma_f32 v[12:13], v[62:63], v[20:21], v[12:13]
	v_pk_mul_f32 v[12:13], v[12:13], v[24:25]
	v_cvt_pk_bf16_f32 v175, v12, v13
	global_store_dwordx4 v[86:87], v[172:175], off offset:-2048
	v_lshl_add_u64 v[64:65], v[64:65], 0, v[10:11]
	v_lshl_add_u64 v[66:67], v[66:67], 0, v[10:11]
	v_lshl_add_u64 v[68:69], v[68:69], 0, v[10:11]
	v_lshl_add_u64 v[70:71], v[70:71], 0, v[10:11]
	v_lshl_add_u64 v[72:73], v[72:73], 0, v[10:11]
	v_lshl_add_u64 v[74:75], v[74:75], 0, v[10:11]
	v_lshl_add_u64 v[76:77], v[76:77], 0, v[10:11]
	v_lshl_add_u64 v[78:79], v[78:79], 0, v[10:11]
	v_lshl_add_u64 v[80:81], v[80:81], 0, v[10:11]
	v_lshl_add_u64 v[82:83], v[82:83], 0, v[10:11]
	v_lshl_add_u64 v[84:85], v[84:85], 0, v[10:11]
	v_lshl_add_u64 v[86:87], v[86:87], 0, v[10:11]
	s_add_i32 s3, s3, 32
	s_add_i32 s2, s2, -1
	s_cmp_lg_u32 s2, 0
	s_cbranch_scc1 .Lfb_loop
	s_branch .LBB0_349
